# GEMM K-loops: M0-hazard s_nop removed by placing the address VALU op between the m0 write and the LDS-DMA (8 issue slots per 2 K-tiles)
# baseline (speedup 1.0000x reference)
.LBB0_116:
	ds_read_b128 v[50:53], v185
	ds_read_b128 v[54:57], v185 offset:1024
	ds_read_b128 v[138:141], v185 offset:2048
	ds_read_b128 v[142:145], v185 offset:3072
	ds_read_b128 v[168:171], v189
	ds_read_b128 v[174:177], v189 offset:1024
	ds_read_b128 v[194:197], v189 offset:2048
	ds_read_b128 v[198:201], v189 offset:3072
	s_add_u32 s60, s52, 0xfff80080
	s_addc_u32 s61, s53, -1
	s_cmp_eq_u32 s64, 28
	s_cselect_b32 s63, s33, s61
	s_cselect_b32 s62, s34, s60
	s_cselect_b32 s61, s35, s51
	s_cselect_b32 s60, s41, s43
	v_lshl_add_u64 v[178:179], s[52:53], 0, v[158:159]
	s_add_i32 m0, s16, 0xc000
	ds_read_b128 v[202:205], v193
	ds_read_b128 v[206:209], v193 offset:1024
	ds_read_b128 v[210:213], v193 offset:2048
	ds_read_b128 v[214:217], v193 offset:3072
	ds_read_b128 v[218:221], v193 offset:4096
	ds_read_b128 v[222:225], v193 offset:5120
	ds_read_b128 v[226:229], v193 offset:6144
	ds_read_b128 v[230:233], v193 offset:7168
	global_load_lds_dwordx4 v[178:179], off
	s_add_i32 m0, s16, 0xe000
	v_lshl_add_u64 v[178:179], s[52:53], 0, v[160:161]
	global_load_lds_dwordx4 v[178:179], off
	s_waitcnt vmcnt(8)
	s_waitcnt lgkmcnt(0)
	s_barrier
	s_setprio 1
	s_waitcnt lgkmcnt(0)
	v_mfma_i32_16x16x64_i8 v[134:137], v[50:53], v[202:205], v[134:137]
	v_mfma_i32_16x16x64_i8 v[130:133], v[138:141], v[202:205], v[130:133]
	v_mfma_i32_16x16x64_i8 v[118:121], v[50:53], v[210:213], v[118:121]
	v_mfma_i32_16x16x64_i8 v[114:117], v[138:141], v[210:213], v[114:117]
	v_mfma_i32_16x16x64_i8 v[102:105], v[50:53], v[218:221], v[102:105]
	v_mfma_i32_16x16x64_i8 v[98:101], v[138:141], v[218:221], v[98:101]
	v_mfma_i32_16x16x64_i8 v[86:89], v[50:53], v[226:229], v[86:89]
	v_mfma_i32_16x16x64_i8 v[82:85], v[138:141], v[226:229], v[82:85]
	v_mfma_i32_16x16x64_i8 v[134:137], v[54:57], v[206:209], v[134:137]
	v_mfma_i32_16x16x64_i8 v[130:133], v[142:145], v[206:209], v[130:133]
	v_mfma_i32_16x16x64_i8 v[118:121], v[54:57], v[214:217], v[118:121]
	v_mfma_i32_16x16x64_i8 v[114:117], v[142:145], v[214:217], v[114:117]
	v_mfma_i32_16x16x64_i8 v[102:105], v[54:57], v[222:225], v[102:105]
	v_mfma_i32_16x16x64_i8 v[98:101], v[142:145], v[222:225], v[98:101]
	v_mfma_i32_16x16x64_i8 v[86:89], v[54:57], v[230:233], v[86:89]
	v_mfma_i32_16x16x64_i8 v[82:85], v[142:145], v[230:233], v[82:85]
	v_mfma_i32_16x16x64_i8 v[126:129], v[168:171], v[202:205], v[126:129]
	v_mfma_i32_16x16x64_i8 v[122:125], v[194:197], v[202:205], v[122:125]
	v_mfma_i32_16x16x64_i8 v[110:113], v[168:171], v[210:213], v[110:113]
	v_mfma_i32_16x16x64_i8 v[106:109], v[194:197], v[210:213], v[106:109]
	v_mfma_i32_16x16x64_i8 v[94:97], v[168:171], v[218:221], v[94:97]
	v_mfma_i32_16x16x64_i8 v[90:93], v[194:197], v[218:221], v[90:93]
	v_mfma_i32_16x16x64_i8 v[78:81], v[168:171], v[226:229], v[78:81]
	v_mfma_i32_16x16x64_i8 v[74:77], v[194:197], v[226:229], v[74:77]
	v_mfma_i32_16x16x64_i8 v[126:129], v[174:177], v[206:209], v[126:129]
	v_mfma_i32_16x16x64_i8 v[122:125], v[198:201], v[206:209], v[122:125]
	v_mfma_i32_16x16x64_i8 v[110:113], v[174:177], v[214:217], v[110:113]
	v_mfma_i32_16x16x64_i8 v[106:109], v[198:201], v[214:217], v[106:109]
	v_mfma_i32_16x16x64_i8 v[94:97], v[174:177], v[222:225], v[94:97]
	v_mfma_i32_16x16x64_i8 v[90:93], v[198:201], v[222:225], v[90:93]
	v_mfma_i32_16x16x64_i8 v[78:81], v[174:177], v[230:233], v[78:81]
	v_mfma_i32_16x16x64_i8 v[74:77], v[198:201], v[230:233], v[74:77]
	s_setprio 0
	s_barrier
	s_add_i32 s65, s24, s14
	v_lshl_add_u64 v[178:179], s[60:61], 0, v[150:151]
	s_mov_b32 m0, s65
	ds_read_b128 v[202:205], v193 offset:16384
	ds_read_b128 v[206:209], v193 offset:17408
	ds_read_b128 v[210:213], v193 offset:18432
	ds_read_b128 v[214:217], v193 offset:19456
	ds_read_b128 v[218:221], v193 offset:20480
	ds_read_b128 v[222:225], v193 offset:21504
	ds_read_b128 v[226:229], v193 offset:22528
	ds_read_b128 v[230:233], v193 offset:23552
	global_load_lds_dwordx4 v[178:179], off
	s_add_i32 m0, s65, 0x2000
	s_add_u32 s66, s60, 0x80000
	v_lshl_add_u64 v[182:183], s[60:61], 0, v[146:147]
	s_addc_u32 s67, s61, 0
	s_add_i32 s65, s25, s14
	global_load_lds_dwordx4 v[182:183], off
	v_lshl_add_u64 v[186:187], s[66:67], 0, v[150:151]
	s_mov_b32 m0, s65
	v_lshl_add_u64 v[190:191], s[62:63], 0, v[148:149]
	global_load_lds_dwordx4 v[186:187], off
	s_add_i32 m0, s65, 0x2000
	v_lshl_add_u64 v[186:187], s[66:67], 0, v[146:147]
	global_load_lds_dwordx4 v[186:187], off
	s_mov_b32 m0, s16
	v_lshl_add_u64 v[186:187], s[62:63], 0, v[152:153]
	global_load_lds_dwordx4 v[186:187], off
	s_mov_b32 m0, s17
	s_nop 0
	global_load_lds_dwordx4 v[190:191], off
	s_waitcnt vmcnt(8)
	s_waitcnt lgkmcnt(0)
	s_barrier
	s_setprio 1
	s_waitcnt lgkmcnt(0)
	v_mfma_i32_16x16x64_i8 v[70:73], v[50:53], v[202:205], v[70:73]
	v_mfma_i32_16x16x64_i8 v[66:69], v[138:141], v[202:205], v[66:69]
	v_mfma_i32_16x16x64_i8 v[46:49], v[50:53], v[210:213], v[46:49]
	v_mfma_i32_16x16x64_i8 v[42:45], v[138:141], v[210:213], v[42:45]
	v_mfma_i32_16x16x64_i8 v[30:33], v[50:53], v[218:221], v[30:33]
	v_mfma_i32_16x16x64_i8 v[26:29], v[138:141], v[218:221], v[26:29]
	v_mfma_i32_16x16x64_i8 v[14:17], v[50:53], v[226:229], v[14:17]
	v_mfma_i32_16x16x64_i8 v[10:13], v[138:141], v[226:229], v[10:13]
	v_mfma_i32_16x16x64_i8 v[70:73], v[54:57], v[206:209], v[70:73]
	v_mfma_i32_16x16x64_i8 v[66:69], v[142:145], v[206:209], v[66:69]
	v_mfma_i32_16x16x64_i8 v[46:49], v[54:57], v[214:217], v[46:49]
	v_mfma_i32_16x16x64_i8 v[42:45], v[142:145], v[214:217], v[42:45]
	v_mfma_i32_16x16x64_i8 v[30:33], v[54:57], v[222:225], v[30:33]
	v_mfma_i32_16x16x64_i8 v[26:29], v[142:145], v[222:225], v[26:29]
	v_mfma_i32_16x16x64_i8 v[14:17], v[54:57], v[230:233], v[14:17]
	v_mfma_i32_16x16x64_i8 v[10:13], v[142:145], v[230:233], v[10:13]
	v_mfma_i32_16x16x64_i8 v[38:41], v[168:171], v[210:213], v[38:41]
	v_mfma_i32_16x16x64_i8 v[34:37], v[194:197], v[210:213], v[34:37]
	v_mfma_i32_16x16x64_i8 v[22:25], v[168:171], v[218:221], v[22:25]
	v_mfma_i32_16x16x64_i8 v[18:21], v[194:197], v[218:221], v[18:21]
	v_mfma_i32_16x16x64_i8 v[6:9], v[168:171], v[226:229], v[6:9]
	v_mfma_i32_16x16x64_i8 v[2:5], v[194:197], v[226:229], v[2:5]
	v_mfma_i32_16x16x64_i8 v[50:53], v[168:171], v[202:205], v[62:65]
	v_mfma_i32_16x16x64_i8 v[54:57], v[194:197], v[202:205], v[58:61]
	v_mfma_i32_16x16x64_i8 v[38:41], v[174:177], v[214:217], v[38:41]
	v_mfma_i32_16x16x64_i8 v[34:37], v[198:201], v[214:217], v[34:37]
	v_mfma_i32_16x16x64_i8 v[22:25], v[174:177], v[222:225], v[22:25]
	v_mfma_i32_16x16x64_i8 v[18:21], v[198:201], v[222:225], v[18:21]
	v_mfma_i32_16x16x64_i8 v[6:9], v[174:177], v[230:233], v[6:9]
	v_mfma_i32_16x16x64_i8 v[2:5], v[198:201], v[230:233], v[2:5]
	v_mfma_i32_16x16x64_i8 v[50:53], v[174:177], v[206:209], v[50:53]
	v_mfma_i32_16x16x64_i8 v[54:57], v[198:201], v[206:209], v[54:57]
	s_setprio 0
	s_barrier
	s_add_i32 s65, 0, 0x18000
	s_add_i32 s66, 0, 0x1c000
	v_add_u32_e32 v142, s65, v173
	v_add_u32_e32 v154, s66, v173
	ds_read_b128 v[58:61], v142
	ds_read_b128 v[62:65], v142 offset:1024
	ds_read_b128 v[138:141], v142 offset:2048
	ds_read_b128 v[142:145], v142 offset:3072
	ds_read_b128 v[168:171], v154
	ds_read_b128 v[174:177], v154 offset:1024
	ds_read_b128 v[194:197], v154 offset:2048
	ds_read_b128 v[198:201], v154 offset:3072
	s_add_u32 s62, s62, 0x80000
	s_addc_u32 s63, s63, 0
	s_mov_b32 m0, s18
	v_lshl_add_u64 v[234:235], s[62:63], 0, v[152:153]
	ds_read_b128 v[202:205], v193 offset:32768
	ds_read_b128 v[206:209], v193 offset:33792
	ds_read_b128 v[210:213], v193 offset:34816
	ds_read_b128 v[214:217], v193 offset:35840
	ds_read_b128 v[218:221], v193 offset:36864
	ds_read_b128 v[222:225], v193 offset:37888
	ds_read_b128 v[226:229], v193 offset:38912
	ds_read_b128 v[230:233], v193 offset:39936
	global_load_lds_dwordx4 v[234:235], off
	s_mov_b32 m0, s19
	v_lshl_add_u64 v[234:235], s[62:63], 0, v[148:149]
	global_load_lds_dwordx4 v[234:235], off
	s_waitcnt vmcnt(8)
	s_waitcnt lgkmcnt(0)
	s_barrier
	s_setprio 1
	s_waitcnt lgkmcnt(0)
	v_mfma_i32_16x16x64_i8 v[134:137], v[58:61], v[202:205], v[134:137]
	v_mfma_i32_16x16x64_i8 v[130:133], v[138:141], v[202:205], v[130:133]
	v_mfma_i32_16x16x64_i8 v[118:121], v[58:61], v[210:213], v[118:121]
	v_mfma_i32_16x16x64_i8 v[114:117], v[138:141], v[210:213], v[114:117]
	v_mfma_i32_16x16x64_i8 v[102:105], v[58:61], v[218:221], v[102:105]
	v_mfma_i32_16x16x64_i8 v[98:101], v[138:141], v[218:221], v[98:101]
	v_mfma_i32_16x16x64_i8 v[86:89], v[58:61], v[226:229], v[86:89]
	v_mfma_i32_16x16x64_i8 v[82:85], v[138:141], v[226:229], v[82:85]
	v_mfma_i32_16x16x64_i8 v[134:137], v[62:65], v[206:209], v[134:137]
	v_mfma_i32_16x16x64_i8 v[130:133], v[142:145], v[206:209], v[130:133]
	v_mfma_i32_16x16x64_i8 v[118:121], v[62:65], v[214:217], v[118:121]
	v_mfma_i32_16x16x64_i8 v[114:117], v[142:145], v[214:217], v[114:117]
	v_mfma_i32_16x16x64_i8 v[102:105], v[62:65], v[222:225], v[102:105]
	v_mfma_i32_16x16x64_i8 v[98:101], v[142:145], v[222:225], v[98:101]
	v_mfma_i32_16x16x64_i8 v[86:89], v[62:65], v[230:233], v[86:89]
	v_mfma_i32_16x16x64_i8 v[82:85], v[142:145], v[230:233], v[82:85]
	v_mfma_i32_16x16x64_i8 v[126:129], v[168:171], v[202:205], v[126:129]
	v_mfma_i32_16x16x64_i8 v[122:125], v[194:197], v[202:205], v[122:125]
	v_mfma_i32_16x16x64_i8 v[110:113], v[168:171], v[210:213], v[110:113]
	v_mfma_i32_16x16x64_i8 v[106:109], v[194:197], v[210:213], v[106:109]
	v_mfma_i32_16x16x64_i8 v[94:97], v[168:171], v[218:221], v[94:97]
	v_mfma_i32_16x16x64_i8 v[90:93], v[194:197], v[218:221], v[90:93]
	v_mfma_i32_16x16x64_i8 v[78:81], v[168:171], v[226:229], v[78:81]
	v_mfma_i32_16x16x64_i8 v[74:77], v[194:197], v[226:229], v[74:77]
	v_mfma_i32_16x16x64_i8 v[126:129], v[174:177], v[206:209], v[126:129]
	v_mfma_i32_16x16x64_i8 v[122:125], v[198:201], v[206:209], v[122:125]
	v_mfma_i32_16x16x64_i8 v[110:113], v[174:177], v[214:217], v[110:113]
	v_mfma_i32_16x16x64_i8 v[106:109], v[198:201], v[214:217], v[106:109]
	v_mfma_i32_16x16x64_i8 v[94:97], v[174:177], v[222:225], v[94:97]
	v_mfma_i32_16x16x64_i8 v[90:93], v[198:201], v[222:225], v[90:93]
	v_mfma_i32_16x16x64_i8 v[78:81], v[174:177], v[230:233], v[78:81]
	v_mfma_i32_16x16x64_i8 v[74:77], v[198:201], v[230:233], v[74:77]
	s_setprio 0
	s_barrier
	s_add_i32 s62, s65, s14
	v_lshl_add_u64 v[178:179], v[178:179], 0, s[36:37]
	s_mov_b32 m0, s62
	ds_read_b128 v[202:205], v193 offset:49152
	ds_read_b128 v[206:209], v193 offset:50176
	ds_read_b128 v[210:213], v193 offset:51200
	ds_read_b128 v[214:217], v193 offset:52224
	ds_read_b128 v[218:221], v193 offset:53248
	ds_read_b128 v[222:225], v193 offset:54272
	ds_read_b128 v[226:229], v193 offset:55296
	ds_read_b128 v[230:233], v193 offset:56320
	global_load_lds_dwordx4 v[178:179], off
	s_add_i32 m0, s62, 0x2000
	s_add_u32 s60, s60, 0x80080
	v_lshl_add_u64 v[178:179], v[182:183], 0, s[36:37]
	s_addc_u32 s61, s61, 0
	s_add_i32 s62, s66, s14
	global_load_lds_dwordx4 v[178:179], off
	s_mov_b32 m0, s62
	v_lshl_add_u64 v[178:179], s[60:61], 0, v[150:151]
	global_load_lds_dwordx4 v[178:179], off
	s_add_i32 m0, s62, 0x2000
	v_lshl_add_u64 v[178:179], s[60:61], 0, v[146:147]
	global_load_lds_dwordx4 v[178:179], off
	s_mov_b32 m0, s21
	v_lshl_add_u64 v[178:179], v[186:187], 0, s[36:37]
	global_load_lds_dwordx4 v[178:179], off
	s_mov_b32 m0, s22
	v_lshl_add_u64 v[178:179], v[190:191], 0, s[36:37]
	global_load_lds_dwordx4 v[178:179], off
	s_waitcnt vmcnt(8)
	s_waitcnt lgkmcnt(0)
	s_barrier
	s_setprio 1
	s_waitcnt lgkmcnt(0)
	v_mfma_i32_16x16x64_i8 v[70:73], v[58:61], v[202:205], v[70:73]
	v_mfma_i32_16x16x64_i8 v[66:69], v[138:141], v[202:205], v[66:69]
	v_mfma_i32_16x16x64_i8 v[46:49], v[58:61], v[210:213], v[46:49]
	v_mfma_i32_16x16x64_i8 v[42:45], v[138:141], v[210:213], v[42:45]
	v_mfma_i32_16x16x64_i8 v[30:33], v[58:61], v[218:221], v[30:33]
	v_mfma_i32_16x16x64_i8 v[26:29], v[138:141], v[218:221], v[26:29]
	v_mfma_i32_16x16x64_i8 v[14:17], v[58:61], v[226:229], v[14:17]
	v_mfma_i32_16x16x64_i8 v[10:13], v[138:141], v[226:229], v[10:13]
	v_mfma_i32_16x16x64_i8 v[70:73], v[62:65], v[206:209], v[70:73]
	v_mfma_i32_16x16x64_i8 v[66:69], v[142:145], v[206:209], v[66:69]
	v_mfma_i32_16x16x64_i8 v[46:49], v[62:65], v[214:217], v[46:49]
	v_mfma_i32_16x16x64_i8 v[42:45], v[142:145], v[214:217], v[42:45]
	v_mfma_i32_16x16x64_i8 v[30:33], v[62:65], v[222:225], v[30:33]
	v_mfma_i32_16x16x64_i8 v[26:29], v[142:145], v[222:225], v[26:29]
	v_mfma_i32_16x16x64_i8 v[14:17], v[62:65], v[230:233], v[14:17]
	v_mfma_i32_16x16x64_i8 v[10:13], v[142:145], v[230:233], v[10:13]
	v_mfma_i32_16x16x64_i8 v[50:53], v[168:171], v[202:205], v[50:53]
	v_mfma_i32_16x16x64_i8 v[62:65], v[174:177], v[206:209], v[50:53]
	v_mfma_i32_16x16x64_i8 v[50:53], v[194:197], v[202:205], v[54:57]
	v_mfma_i32_16x16x64_i8 v[38:41], v[168:171], v[210:213], v[38:41]
	v_mfma_i32_16x16x64_i8 v[34:37], v[194:197], v[210:213], v[34:37]
	v_mfma_i32_16x16x64_i8 v[22:25], v[168:171], v[218:221], v[22:25]
	v_mfma_i32_16x16x64_i8 v[18:21], v[194:197], v[218:221], v[18:21]
	v_mfma_i32_16x16x64_i8 v[6:9], v[168:171], v[226:229], v[6:9]
	v_mfma_i32_16x16x64_i8 v[2:5], v[194:197], v[226:229], v[2:5]
	v_mfma_i32_16x16x64_i8 v[58:61], v[198:201], v[206:209], v[50:53]
	v_mfma_i32_16x16x64_i8 v[38:41], v[174:177], v[214:217], v[38:41]
	v_mfma_i32_16x16x64_i8 v[34:37], v[198:201], v[214:217], v[34:37]
	v_mfma_i32_16x16x64_i8 v[22:25], v[174:177], v[222:225], v[22:25]
	v_mfma_i32_16x16x64_i8 v[18:21], v[198:201], v[222:225], v[18:21]
	v_mfma_i32_16x16x64_i8 v[6:9], v[174:177], v[230:233], v[6:9]
	v_mfma_i32_16x16x64_i8 v[2:5], v[198:201], v[230:233], v[2:5]
	s_setprio 0
	s_barrier
	s_add_i32 s64, s64, 2
	s_add_u32 s52, s52, 0x100
	s_addc_u32 s53, s53, 0
	s_add_u32 s43, s43, 0x100
	s_addc_u32 s51, s51, 0
	s_cmp_lt_u32 s64, 30
	s_cbranch_scc1 .LBB0_116
	s_nop 0
	s_nop 0
	s_nop 0
	s_nop 0
	s_nop 0
	s_nop 0
	s_nop 0
	s_nop 0
	s_nop 0
	s_nop 0
	s_nop 0
	s_nop 0
	s_nop 0
	s_nop 0
	s_nop 0
	s_nop 0
	s_andn2_b64 vcc, exec, s[38:39]
	s_cbranch_vccnz .LBB0_119
	s_barrier

.LBB0_256:
	ds_read_b128 v[126:129], v175
	ds_read_b128 v[130:133], v175 offset:1024
	ds_read_b128 v[138:141], v175 offset:2048
	ds_read_b128 v[142:145], v175 offset:3072
	ds_read_b128 v[164:167], v176
	ds_read_b128 v[168:171], v176 offset:1024
	ds_read_b128 v[178:181], v176 offset:2048
	ds_read_b128 v[182:185], v176 offset:3072
	s_add_u32 s48, s46, 0xffea8080
	s_addc_u32 s49, s47, -1
	s_cmpk_eq_i32 s52, 0x52
	s_cselect_b32 s51, s5, s49
	s_cselect_b32 s50, s4, s48
	s_cselect_b32 s49, s43, s35
	s_cselect_b32 s48, s42, s34
	v_lshl_add_u64 v[218:219], s[46:47], 0, v[156:157]
	s_add_i32 m0, s15, 0xc000
	ds_read_b128 v[186:189], v177
	ds_read_b128 v[190:193], v177 offset:1024
	ds_read_b128 v[194:197], v177 offset:2048
	ds_read_b128 v[198:201], v177 offset:3072
	ds_read_b128 v[202:205], v177 offset:4096
	ds_read_b128 v[206:209], v177 offset:5120
	ds_read_b128 v[210:213], v177 offset:6144
	ds_read_b128 v[214:217], v177 offset:7168
	global_load_lds_dwordx4 v[218:219], off
	s_add_i32 m0, s15, 0xe000
	v_lshl_add_u64 v[218:219], s[46:47], 0, v[158:159]
	global_load_lds_dwordx4 v[218:219], off
	s_waitcnt vmcnt(8)
	s_waitcnt lgkmcnt(0)
	s_barrier
	s_setprio 1
	s_waitcnt lgkmcnt(0)
	v_mfma_i32_16x16x64_i8 v[134:137], v[126:129], v[186:189], v[134:137]
	v_mfma_i32_16x16x64_i8 v[122:125], v[138:141], v[186:189], v[122:125]
	v_mfma_i32_16x16x64_i8 v[110:113], v[126:129], v[194:197], v[110:113]
	v_mfma_i32_16x16x64_i8 v[106:109], v[138:141], v[194:197], v[106:109]
	v_mfma_i32_16x16x64_i8 v[94:97], v[126:129], v[202:205], v[94:97]
	v_mfma_i32_16x16x64_i8 v[90:93], v[138:141], v[202:205], v[90:93]
	v_mfma_i32_16x16x64_i8 v[78:81], v[126:129], v[210:213], v[78:81]
	v_mfma_i32_16x16x64_i8 v[74:77], v[138:141], v[210:213], v[74:77]
	v_mfma_i32_16x16x64_i8 v[134:137], v[130:133], v[190:193], v[134:137]
	v_mfma_i32_16x16x64_i8 v[122:125], v[142:145], v[190:193], v[122:125]
	v_mfma_i32_16x16x64_i8 v[110:113], v[130:133], v[198:201], v[110:113]
	v_mfma_i32_16x16x64_i8 v[106:109], v[142:145], v[198:201], v[106:109]
	v_mfma_i32_16x16x64_i8 v[94:97], v[130:133], v[206:209], v[94:97]
	v_mfma_i32_16x16x64_i8 v[90:93], v[142:145], v[206:209], v[90:93]
	v_mfma_i32_16x16x64_i8 v[78:81], v[130:133], v[214:217], v[78:81]
	v_mfma_i32_16x16x64_i8 v[74:77], v[142:145], v[214:217], v[74:77]
	v_mfma_i32_16x16x64_i8 v[118:121], v[164:167], v[186:189], v[118:121]
	v_mfma_i32_16x16x64_i8 v[114:117], v[178:181], v[186:189], v[114:117]
	v_mfma_i32_16x16x64_i8 v[102:105], v[164:167], v[194:197], v[102:105]
	v_mfma_i32_16x16x64_i8 v[98:101], v[178:181], v[194:197], v[98:101]
	v_mfma_i32_16x16x64_i8 v[86:89], v[164:167], v[202:205], v[86:89]
	v_mfma_i32_16x16x64_i8 v[82:85], v[178:181], v[202:205], v[82:85]
	v_mfma_i32_16x16x64_i8 v[70:73], v[164:167], v[210:213], v[70:73]
	v_mfma_i32_16x16x64_i8 v[66:69], v[178:181], v[210:213], v[66:69]
	v_mfma_i32_16x16x64_i8 v[118:121], v[168:171], v[190:193], v[118:121]
	v_mfma_i32_16x16x64_i8 v[114:117], v[182:185], v[190:193], v[114:117]
	v_mfma_i32_16x16x64_i8 v[102:105], v[168:171], v[198:201], v[102:105]
	v_mfma_i32_16x16x64_i8 v[98:101], v[182:185], v[198:201], v[98:101]
	v_mfma_i32_16x16x64_i8 v[86:89], v[168:171], v[206:209], v[86:89]
	v_mfma_i32_16x16x64_i8 v[82:85], v[182:185], v[206:209], v[82:85]
	v_mfma_i32_16x16x64_i8 v[70:73], v[168:171], v[214:217], v[70:73]
	v_mfma_i32_16x16x64_i8 v[66:69], v[182:185], v[214:217], v[66:69]
	s_setprio 0
	s_barrier
	s_add_i32 s53, s23, s12
	v_lshl_add_u64 v[218:219], s[48:49], 0, v[150:151]
	s_mov_b32 m0, s53
	ds_read_b128 v[186:189], v177 offset:16384
	ds_read_b128 v[190:193], v177 offset:17408
	ds_read_b128 v[194:197], v177 offset:18432
	ds_read_b128 v[198:201], v177 offset:19456
	ds_read_b128 v[202:205], v177 offset:20480
	ds_read_b128 v[206:209], v177 offset:21504
	ds_read_b128 v[210:213], v177 offset:22528
	ds_read_b128 v[214:217], v177 offset:23552
	global_load_lds_dwordx4 v[218:219], off
	s_add_i32 m0, s53, 0x2000
	s_add_u32 s60, s48, 0x158000
	v_lshl_add_u64 v[220:221], s[48:49], 0, v[146:147]
	s_addc_u32 s61, s49, 0
	s_add_i32 s53, s24, s12
	global_load_lds_dwordx4 v[220:221], off
	v_lshl_add_u64 v[222:223], s[60:61], 0, v[150:151]
	s_mov_b32 m0, s53
	v_lshl_add_u64 v[224:225], s[50:51], 0, v[148:149]
	global_load_lds_dwordx4 v[222:223], off
	s_add_i32 m0, s53, 0x2000
	v_lshl_add_u64 v[222:223], s[60:61], 0, v[146:147]
	global_load_lds_dwordx4 v[222:223], off
	s_mov_b32 m0, s15
	v_lshl_add_u64 v[222:223], s[50:51], 0, v[152:153]
	global_load_lds_dwordx4 v[222:223], off
	s_mov_b32 m0, s16
	s_nop 0
	global_load_lds_dwordx4 v[224:225], off
	s_waitcnt vmcnt(8)
	s_waitcnt lgkmcnt(0)
	s_barrier
	s_setprio 1
	s_waitcnt lgkmcnt(0)
	v_mfma_i32_16x16x64_i8 v[62:65], v[126:129], v[186:189], v[62:65]
	v_mfma_i32_16x16x64_i8 v[58:61], v[138:141], v[186:189], v[58:61]
	v_mfma_i32_16x16x64_i8 v[46:49], v[126:129], v[194:197], v[46:49]
	v_mfma_i32_16x16x64_i8 v[42:45], v[138:141], v[194:197], v[42:45]
	v_mfma_i32_16x16x64_i8 v[30:33], v[126:129], v[202:205], v[30:33]
	v_mfma_i32_16x16x64_i8 v[26:29], v[138:141], v[202:205], v[26:29]
	v_mfma_i32_16x16x64_i8 v[14:17], v[126:129], v[210:213], v[14:17]
	v_mfma_i32_16x16x64_i8 v[10:13], v[138:141], v[210:213], v[10:13]
	v_mfma_i32_16x16x64_i8 v[62:65], v[130:133], v[190:193], v[62:65]
	v_mfma_i32_16x16x64_i8 v[58:61], v[142:145], v[190:193], v[58:61]
	v_mfma_i32_16x16x64_i8 v[46:49], v[130:133], v[198:201], v[46:49]
	v_mfma_i32_16x16x64_i8 v[42:45], v[142:145], v[198:201], v[42:45]
	v_mfma_i32_16x16x64_i8 v[30:33], v[130:133], v[206:209], v[30:33]
	v_mfma_i32_16x16x64_i8 v[26:29], v[142:145], v[206:209], v[26:29]
	v_mfma_i32_16x16x64_i8 v[14:17], v[130:133], v[214:217], v[14:17]
	v_mfma_i32_16x16x64_i8 v[10:13], v[142:145], v[214:217], v[10:13]
	v_mfma_i32_16x16x64_i8 v[54:57], v[164:167], v[186:189], v[54:57]
	v_mfma_i32_16x16x64_i8 v[50:53], v[178:181], v[186:189], v[50:53]
	v_mfma_i32_16x16x64_i8 v[38:41], v[164:167], v[194:197], v[38:41]
	v_mfma_i32_16x16x64_i8 v[34:37], v[178:181], v[194:197], v[34:37]
	v_mfma_i32_16x16x64_i8 v[22:25], v[164:167], v[202:205], v[22:25]
	v_mfma_i32_16x16x64_i8 v[18:21], v[178:181], v[202:205], v[18:21]
	v_mfma_i32_16x16x64_i8 v[6:9], v[164:167], v[210:213], v[6:9]
	v_mfma_i32_16x16x64_i8 v[2:5], v[178:181], v[210:213], v[2:5]
	v_mfma_i32_16x16x64_i8 v[54:57], v[168:171], v[190:193], v[54:57]
	v_mfma_i32_16x16x64_i8 v[50:53], v[182:185], v[190:193], v[50:53]
	v_mfma_i32_16x16x64_i8 v[38:41], v[168:171], v[198:201], v[38:41]
	v_mfma_i32_16x16x64_i8 v[34:37], v[182:185], v[198:201], v[34:37]
	v_mfma_i32_16x16x64_i8 v[22:25], v[168:171], v[206:209], v[22:25]
	v_mfma_i32_16x16x64_i8 v[18:21], v[182:185], v[206:209], v[18:21]
	v_mfma_i32_16x16x64_i8 v[6:9], v[168:171], v[214:217], v[6:9]
	v_mfma_i32_16x16x64_i8 v[2:5], v[182:185], v[214:217], v[2:5]
	s_setprio 0
	s_barrier
	s_add_i32 s53, 0, 0x18000
	s_add_i32 s60, 0, 0x1c000
	v_add_u32_e32 v142, s53, v173
	v_add_u32_e32 v154, s60, v173
	ds_read_b128 v[126:129], v142
	ds_read_b128 v[130:133], v142 offset:1024
	ds_read_b128 v[138:141], v142 offset:2048
	ds_read_b128 v[142:145], v142 offset:3072
	ds_read_b128 v[164:167], v154
	ds_read_b128 v[168:171], v154 offset:1024
	ds_read_b128 v[178:181], v154 offset:2048
	ds_read_b128 v[182:185], v154 offset:3072
	s_add_u32 s50, s50, 0x158000
	s_addc_u32 s51, s51, 0
	s_mov_b32 m0, s17
	v_lshl_add_u64 v[226:227], s[50:51], 0, v[152:153]
	ds_read_b128 v[186:189], v177 offset:32768
	ds_read_b128 v[190:193], v177 offset:33792
	ds_read_b128 v[194:197], v177 offset:34816
	ds_read_b128 v[198:201], v177 offset:35840
	ds_read_b128 v[202:205], v177 offset:36864
	ds_read_b128 v[206:209], v177 offset:37888
	ds_read_b128 v[210:213], v177 offset:38912
	ds_read_b128 v[214:217], v177 offset:39936
	global_load_lds_dwordx4 v[226:227], off
	s_mov_b32 m0, s18
	v_lshl_add_u64 v[226:227], s[50:51], 0, v[148:149]
	global_load_lds_dwordx4 v[226:227], off
	s_waitcnt vmcnt(8)
	s_waitcnt lgkmcnt(0)
	s_barrier
	s_setprio 1
	s_waitcnt lgkmcnt(0)
	v_mfma_i32_16x16x64_i8 v[134:137], v[126:129], v[186:189], v[134:137]
	v_mfma_i32_16x16x64_i8 v[122:125], v[138:141], v[186:189], v[122:125]
	v_mfma_i32_16x16x64_i8 v[110:113], v[126:129], v[194:197], v[110:113]
	v_mfma_i32_16x16x64_i8 v[106:109], v[138:141], v[194:197], v[106:109]
	v_mfma_i32_16x16x64_i8 v[94:97], v[126:129], v[202:205], v[94:97]
	v_mfma_i32_16x16x64_i8 v[90:93], v[138:141], v[202:205], v[90:93]
	v_mfma_i32_16x16x64_i8 v[78:81], v[126:129], v[210:213], v[78:81]
	v_mfma_i32_16x16x64_i8 v[74:77], v[138:141], v[210:213], v[74:77]
	v_mfma_i32_16x16x64_i8 v[134:137], v[130:133], v[190:193], v[134:137]
	v_mfma_i32_16x16x64_i8 v[122:125], v[142:145], v[190:193], v[122:125]
	v_mfma_i32_16x16x64_i8 v[110:113], v[130:133], v[198:201], v[110:113]
	v_mfma_i32_16x16x64_i8 v[106:109], v[142:145], v[198:201], v[106:109]
	v_mfma_i32_16x16x64_i8 v[94:97], v[130:133], v[206:209], v[94:97]
	v_mfma_i32_16x16x64_i8 v[90:93], v[142:145], v[206:209], v[90:93]
	v_mfma_i32_16x16x64_i8 v[78:81], v[130:133], v[214:217], v[78:81]
	v_mfma_i32_16x16x64_i8 v[74:77], v[142:145], v[214:217], v[74:77]
	v_mfma_i32_16x16x64_i8 v[118:121], v[164:167], v[186:189], v[118:121]
	v_mfma_i32_16x16x64_i8 v[114:117], v[178:181], v[186:189], v[114:117]
	v_mfma_i32_16x16x64_i8 v[102:105], v[164:167], v[194:197], v[102:105]
	v_mfma_i32_16x16x64_i8 v[98:101], v[178:181], v[194:197], v[98:101]
	v_mfma_i32_16x16x64_i8 v[86:89], v[164:167], v[202:205], v[86:89]
	v_mfma_i32_16x16x64_i8 v[82:85], v[178:181], v[202:205], v[82:85]
	v_mfma_i32_16x16x64_i8 v[70:73], v[164:167], v[210:213], v[70:73]
	v_mfma_i32_16x16x64_i8 v[66:69], v[178:181], v[210:213], v[66:69]
	v_mfma_i32_16x16x64_i8 v[118:121], v[168:171], v[190:193], v[118:121]
	v_mfma_i32_16x16x64_i8 v[114:117], v[182:185], v[190:193], v[114:117]
	v_mfma_i32_16x16x64_i8 v[102:105], v[168:171], v[198:201], v[102:105]
	v_mfma_i32_16x16x64_i8 v[98:101], v[182:185], v[198:201], v[98:101]
	v_mfma_i32_16x16x64_i8 v[86:89], v[168:171], v[206:209], v[86:89]
	v_mfma_i32_16x16x64_i8 v[82:85], v[182:185], v[206:209], v[82:85]
	v_mfma_i32_16x16x64_i8 v[70:73], v[168:171], v[214:217], v[70:73]
	v_mfma_i32_16x16x64_i8 v[66:69], v[182:185], v[214:217], v[66:69]
	s_setprio 0
	s_barrier
	s_add_i32 s50, s53, s12
	v_lshl_add_u64 v[218:219], v[218:219], 0, s[38:39]
	s_mov_b32 m0, s50
	ds_read_b128 v[186:189], v177 offset:49152
	ds_read_b128 v[190:193], v177 offset:50176
	ds_read_b128 v[194:197], v177 offset:51200
	ds_read_b128 v[198:201], v177 offset:52224
	ds_read_b128 v[202:205], v177 offset:53248
	ds_read_b128 v[206:209], v177 offset:54272
	ds_read_b128 v[210:213], v177 offset:55296
	ds_read_b128 v[214:217], v177 offset:56320
	global_load_lds_dwordx4 v[218:219], off
	s_add_i32 m0, s50, 0x2000
	s_add_u32 s48, s48, 0x158080
	v_lshl_add_u64 v[218:219], v[220:221], 0, s[38:39]
	s_addc_u32 s49, s49, 0
	s_add_i32 s50, s60, s12
	global_load_lds_dwordx4 v[218:219], off
	s_mov_b32 m0, s50
	v_lshl_add_u64 v[218:219], s[48:49], 0, v[150:151]
	global_load_lds_dwordx4 v[218:219], off
	s_add_i32 m0, s50, 0x2000
	v_lshl_add_u64 v[218:219], s[48:49], 0, v[146:147]
	global_load_lds_dwordx4 v[218:219], off
	s_mov_b32 m0, s20
	v_lshl_add_u64 v[218:219], v[222:223], 0, s[38:39]
	global_load_lds_dwordx4 v[218:219], off
	s_mov_b32 m0, s21
	v_lshl_add_u64 v[218:219], v[224:225], 0, s[38:39]
	global_load_lds_dwordx4 v[218:219], off
	s_waitcnt vmcnt(8)
	s_waitcnt lgkmcnt(0)
	s_barrier
	s_setprio 1
	s_waitcnt lgkmcnt(0)
	v_mfma_i32_16x16x64_i8 v[62:65], v[126:129], v[186:189], v[62:65]
	v_mfma_i32_16x16x64_i8 v[58:61], v[138:141], v[186:189], v[58:61]
	v_mfma_i32_16x16x64_i8 v[46:49], v[126:129], v[194:197], v[46:49]
	v_mfma_i32_16x16x64_i8 v[42:45], v[138:141], v[194:197], v[42:45]
	v_mfma_i32_16x16x64_i8 v[30:33], v[126:129], v[202:205], v[30:33]
	v_mfma_i32_16x16x64_i8 v[26:29], v[138:141], v[202:205], v[26:29]
	v_mfma_i32_16x16x64_i8 v[14:17], v[126:129], v[210:213], v[14:17]
	v_mfma_i32_16x16x64_i8 v[10:13], v[138:141], v[210:213], v[10:13]
	v_mfma_i32_16x16x64_i8 v[62:65], v[130:133], v[190:193], v[62:65]
	v_mfma_i32_16x16x64_i8 v[58:61], v[142:145], v[190:193], v[58:61]
	v_mfma_i32_16x16x64_i8 v[46:49], v[130:133], v[198:201], v[46:49]
	v_mfma_i32_16x16x64_i8 v[42:45], v[142:145], v[198:201], v[42:45]
	v_mfma_i32_16x16x64_i8 v[30:33], v[130:133], v[206:209], v[30:33]
	v_mfma_i32_16x16x64_i8 v[26:29], v[142:145], v[206:209], v[26:29]
	v_mfma_i32_16x16x64_i8 v[14:17], v[130:133], v[214:217], v[14:17]
	v_mfma_i32_16x16x64_i8 v[10:13], v[142:145], v[214:217], v[10:13]
	v_mfma_i32_16x16x64_i8 v[54:57], v[164:167], v[186:189], v[54:57]
	v_mfma_i32_16x16x64_i8 v[50:53], v[178:181], v[186:189], v[50:53]
	v_mfma_i32_16x16x64_i8 v[38:41], v[164:167], v[194:197], v[38:41]
	v_mfma_i32_16x16x64_i8 v[34:37], v[178:181], v[194:197], v[34:37]
	v_mfma_i32_16x16x64_i8 v[22:25], v[164:167], v[202:205], v[22:25]
	v_mfma_i32_16x16x64_i8 v[18:21], v[178:181], v[202:205], v[18:21]
	v_mfma_i32_16x16x64_i8 v[6:9], v[164:167], v[210:213], v[6:9]
	v_mfma_i32_16x16x64_i8 v[2:5], v[178:181], v[210:213], v[2:5]
	v_mfma_i32_16x16x64_i8 v[54:57], v[168:171], v[190:193], v[54:57]
	v_mfma_i32_16x16x64_i8 v[50:53], v[182:185], v[190:193], v[50:53]
	v_mfma_i32_16x16x64_i8 v[38:41], v[168:171], v[198:201], v[38:41]
	v_mfma_i32_16x16x64_i8 v[34:37], v[182:185], v[198:201], v[34:37]
	v_mfma_i32_16x16x64_i8 v[22:25], v[168:171], v[206:209], v[22:25]
	v_mfma_i32_16x16x64_i8 v[18:21], v[182:185], v[206:209], v[18:21]
	v_mfma_i32_16x16x64_i8 v[6:9], v[168:171], v[214:217], v[6:9]
	v_mfma_i32_16x16x64_i8 v[2:5], v[182:185], v[214:217], v[2:5]
	s_setprio 0
	s_barrier
	s_add_i32 s52, s52, 2
	s_add_u32 s46, s46, 0x100
	s_addc_u32 s47, s47, 0
	s_add_u32 s34, s34, 0x100
	s_addc_u32 s35, s35, 0
	s_cmpk_lt_u32 s52, 0x54
	s_cbranch_scc1 .LBB0_256
	s_nop 0
	s_nop 0
	s_nop 0
	s_nop 0
	s_nop 0
	s_nop 0
	s_nop 0
	s_nop 0
	s_nop 0
	s_nop 0
	s_nop 0
	s_nop 0
	s_nop 0
	s_nop 0
	s_nop 0
	s_nop 0
	s_andn2_b64 vcc, exec, s[40:41]
	s_cbranch_vccnz .LBB0_259
	s_barrier

.LBB0_429:
	ds_read_b128 v[74:77], v173
	ds_read_b128 v[78:81], v173 offset:1024
	ds_read_b128 v[90:93], v173 offset:2048
	ds_read_b128 v[94:97], v173 offset:3072
	ds_read_b128 v[164:167], v174
	ds_read_b128 v[176:179], v174 offset:1024
	ds_read_b128 v[180:183], v174 offset:2048
	ds_read_b128 v[184:187], v174 offset:3072
	s_add_u32 s50, s48, 0xfff80080
	s_addc_u32 s51, s49, -1
	s_cmp_eq_u32 s61, 28
	s_cselect_b32 s53, s39, s51
	s_cselect_b32 s52, s47, s50
	s_cselect_b32 s51, s37, s60
	s_cselect_b32 s50, s56, s57
	v_lshl_add_u64 v[168:169], s[48:49], 0, v[158:159]
	s_add_i32 m0, s19, 0xc000
	ds_read_b128 v[188:191], v175
	ds_read_b128 v[192:195], v175 offset:1024
	ds_read_b128 v[196:199], v175 offset:2048
	ds_read_b128 v[200:203], v175 offset:3072
	ds_read_b128 v[204:207], v175 offset:4096
	ds_read_b128 v[208:211], v175 offset:5120
	ds_read_b128 v[212:215], v175 offset:6144
	ds_read_b128 v[216:219], v175 offset:7168
	global_load_lds_dwordx4 v[168:169], off
	s_add_i32 m0, s19, 0xe000
	v_lshl_add_u64 v[168:169], s[48:49], 0, v[160:161]
	global_load_lds_dwordx4 v[168:169], off
	s_waitcnt vmcnt(8)
	s_waitcnt lgkmcnt(0)
	s_barrier
	s_setprio 1
	s_waitcnt lgkmcnt(0)
	v_mfma_i32_16x16x64_i8 v[142:145], v[74:77], v[188:191], v[142:145]
	v_mfma_i32_16x16x64_i8 v[138:141], v[90:93], v[188:191], v[138:141]
	v_mfma_i32_16x16x64_i8 v[126:129], v[74:77], v[196:199], v[126:129]
	v_mfma_i32_16x16x64_i8 v[122:125], v[90:93], v[196:199], v[122:125]
	v_mfma_i32_16x16x64_i8 v[110:113], v[74:77], v[204:207], v[110:113]
	v_mfma_i32_16x16x64_i8 v[106:109], v[90:93], v[204:207], v[106:109]
	v_mfma_i32_16x16x64_i8 v[86:89], v[74:77], v[212:215], v[86:89]
	v_mfma_i32_16x16x64_i8 v[82:85], v[90:93], v[212:215], v[82:85]
	v_mfma_i32_16x16x64_i8 v[142:145], v[78:81], v[192:195], v[142:145]
	v_mfma_i32_16x16x64_i8 v[138:141], v[94:97], v[192:195], v[138:141]
	v_mfma_i32_16x16x64_i8 v[126:129], v[78:81], v[200:203], v[126:129]
	v_mfma_i32_16x16x64_i8 v[122:125], v[94:97], v[200:203], v[122:125]
	v_mfma_i32_16x16x64_i8 v[110:113], v[78:81], v[208:211], v[110:113]
	v_mfma_i32_16x16x64_i8 v[106:109], v[94:97], v[208:211], v[106:109]
	v_mfma_i32_16x16x64_i8 v[86:89], v[78:81], v[216:219], v[86:89]
	v_mfma_i32_16x16x64_i8 v[82:85], v[94:97], v[216:219], v[82:85]
	v_mfma_i32_16x16x64_i8 v[134:137], v[164:167], v[188:191], v[134:137]
	v_mfma_i32_16x16x64_i8 v[130:133], v[180:183], v[188:191], v[130:133]
	v_mfma_i32_16x16x64_i8 v[118:121], v[164:167], v[196:199], v[118:121]
	v_mfma_i32_16x16x64_i8 v[114:117], v[180:183], v[196:199], v[114:117]
	v_mfma_i32_16x16x64_i8 v[102:105], v[164:167], v[204:207], v[102:105]
	v_mfma_i32_16x16x64_i8 v[98:101], v[180:183], v[204:207], v[98:101]
	v_mfma_i32_16x16x64_i8 v[70:73], v[164:167], v[212:215], v[70:73]
	v_mfma_i32_16x16x64_i8 v[66:69], v[180:183], v[212:215], v[66:69]
	v_mfma_i32_16x16x64_i8 v[134:137], v[176:179], v[192:195], v[134:137]
	v_mfma_i32_16x16x64_i8 v[130:133], v[184:187], v[192:195], v[130:133]
	v_mfma_i32_16x16x64_i8 v[118:121], v[176:179], v[200:203], v[118:121]
	v_mfma_i32_16x16x64_i8 v[114:117], v[184:187], v[200:203], v[114:117]
	v_mfma_i32_16x16x64_i8 v[102:105], v[176:179], v[208:211], v[102:105]
	v_mfma_i32_16x16x64_i8 v[98:101], v[184:187], v[208:211], v[98:101]
	v_mfma_i32_16x16x64_i8 v[70:73], v[176:179], v[216:219], v[70:73]
	v_mfma_i32_16x16x64_i8 v[66:69], v[184:187], v[216:219], v[66:69]
	s_setprio 0
	s_barrier
	s_add_i32 s62, s35, s13
	v_lshl_add_u64 v[168:169], s[50:51], 0, v[148:149]
	s_mov_b32 m0, s62
	ds_read_b128 v[188:191], v175 offset:16384
	ds_read_b128 v[192:195], v175 offset:17408
	ds_read_b128 v[196:199], v175 offset:18432
	ds_read_b128 v[200:203], v175 offset:19456
	ds_read_b128 v[204:207], v175 offset:20480
	ds_read_b128 v[208:211], v175 offset:21504
	ds_read_b128 v[212:215], v175 offset:22528
	ds_read_b128 v[216:219], v175 offset:23552
	global_load_lds_dwordx4 v[168:169], off
	s_add_i32 m0, s62, 0x2000
	s_add_u32 s62, s50, 0x80000
	v_lshl_add_u64 v[220:221], s[50:51], 0, v[152:153]
	s_addc_u32 s63, s51, 0
	s_add_i32 s64, s54, s13
	global_load_lds_dwordx4 v[220:221], off
	v_lshl_add_u64 v[222:223], s[62:63], 0, v[148:149]
	s_mov_b32 m0, s64
	v_lshl_add_u64 v[224:225], s[52:53], 0, v[150:151]
	global_load_lds_dwordx4 v[222:223], off
	s_add_i32 m0, s64, 0x2000
	v_lshl_add_u64 v[222:223], s[62:63], 0, v[152:153]
	global_load_lds_dwordx4 v[222:223], off
	s_mov_b32 m0, s19
	v_lshl_add_u64 v[222:223], s[52:53], 0, v[146:147]
	global_load_lds_dwordx4 v[222:223], off
	s_mov_b32 m0, s20
	s_nop 0
	global_load_lds_dwordx4 v[224:225], off
	s_waitcnt vmcnt(8)
	s_waitcnt lgkmcnt(0)
	s_barrier
	s_setprio 1
	s_waitcnt lgkmcnt(0)
	v_mfma_i32_16x16x64_i8 v[62:65], v[74:77], v[188:191], v[62:65]
	v_mfma_i32_16x16x64_i8 v[58:61], v[90:93], v[188:191], v[58:61]
	v_mfma_i32_16x16x64_i8 v[46:49], v[74:77], v[196:199], v[46:49]
	v_mfma_i32_16x16x64_i8 v[42:45], v[90:93], v[196:199], v[42:45]
	v_mfma_i32_16x16x64_i8 v[30:33], v[74:77], v[204:207], v[30:33]
	v_mfma_i32_16x16x64_i8 v[26:29], v[90:93], v[204:207], v[26:29]
	v_mfma_i32_16x16x64_i8 v[14:17], v[74:77], v[212:215], v[14:17]
	v_mfma_i32_16x16x64_i8 v[10:13], v[90:93], v[212:215], v[10:13]
	v_mfma_i32_16x16x64_i8 v[62:65], v[78:81], v[192:195], v[62:65]
	v_mfma_i32_16x16x64_i8 v[58:61], v[94:97], v[192:195], v[58:61]
	v_mfma_i32_16x16x64_i8 v[46:49], v[78:81], v[200:203], v[46:49]
	v_mfma_i32_16x16x64_i8 v[42:45], v[94:97], v[200:203], v[42:45]
	v_mfma_i32_16x16x64_i8 v[30:33], v[78:81], v[208:211], v[30:33]
	v_mfma_i32_16x16x64_i8 v[26:29], v[94:97], v[208:211], v[26:29]
	v_mfma_i32_16x16x64_i8 v[14:17], v[78:81], v[216:219], v[14:17]
	v_mfma_i32_16x16x64_i8 v[10:13], v[94:97], v[216:219], v[10:13]
	v_mfma_i32_16x16x64_i8 v[54:57], v[164:167], v[188:191], v[54:57]
	v_mfma_i32_16x16x64_i8 v[50:53], v[180:183], v[188:191], v[50:53]
	v_mfma_i32_16x16x64_i8 v[38:41], v[164:167], v[196:199], v[38:41]
	v_mfma_i32_16x16x64_i8 v[34:37], v[180:183], v[196:199], v[34:37]
	v_mfma_i32_16x16x64_i8 v[22:25], v[164:167], v[204:207], v[22:25]
	v_mfma_i32_16x16x64_i8 v[18:21], v[180:183], v[204:207], v[18:21]
	v_mfma_i32_16x16x64_i8 v[6:9], v[164:167], v[212:215], v[6:9]
	v_mfma_i32_16x16x64_i8 v[2:5], v[180:183], v[212:215], v[2:5]
	v_mfma_i32_16x16x64_i8 v[54:57], v[176:179], v[192:195], v[54:57]
	v_mfma_i32_16x16x64_i8 v[50:53], v[184:187], v[192:195], v[50:53]
	v_mfma_i32_16x16x64_i8 v[38:41], v[176:179], v[200:203], v[38:41]
	v_mfma_i32_16x16x64_i8 v[34:37], v[184:187], v[200:203], v[34:37]
	v_mfma_i32_16x16x64_i8 v[22:25], v[176:179], v[208:211], v[22:25]
	v_mfma_i32_16x16x64_i8 v[18:21], v[184:187], v[208:211], v[18:21]
	v_mfma_i32_16x16x64_i8 v[6:9], v[176:179], v[216:219], v[6:9]
	v_mfma_i32_16x16x64_i8 v[2:5], v[184:187], v[216:219], v[2:5]
	s_setprio 0
	s_barrier
	s_add_i32 s62, 0, 0x18000
	s_add_i32 s63, 0, 0x1c000
	v_add_u32_e32 v94, s62, v171
	v_add_u32_e32 v184, s63, v171
	ds_read_b128 v[74:77], v94
	ds_read_b128 v[78:81], v94 offset:1024
	ds_read_b128 v[90:93], v94 offset:2048
	ds_read_b128 v[94:97], v94 offset:3072
	ds_read_b128 v[164:167], v184
	ds_read_b128 v[176:179], v184 offset:1024
	ds_read_b128 v[180:183], v184 offset:2048
	ds_read_b128 v[184:187], v184 offset:3072
	s_add_u32 s52, s52, 0x80000
	s_addc_u32 s53, s53, 0
	s_mov_b32 m0, s21
	v_lshl_add_u64 v[226:227], s[52:53], 0, v[146:147]
	ds_read_b128 v[188:191], v175 offset:32768
	ds_read_b128 v[192:195], v175 offset:33792
	ds_read_b128 v[196:199], v175 offset:34816
	ds_read_b128 v[200:203], v175 offset:35840
	ds_read_b128 v[204:207], v175 offset:36864
	ds_read_b128 v[208:211], v175 offset:37888
	ds_read_b128 v[212:215], v175 offset:38912
	ds_read_b128 v[216:219], v175 offset:39936
	global_load_lds_dwordx4 v[226:227], off
	s_mov_b32 m0, s22
	v_lshl_add_u64 v[226:227], s[52:53], 0, v[150:151]
	global_load_lds_dwordx4 v[226:227], off
	s_waitcnt vmcnt(8)
	s_waitcnt lgkmcnt(0)
	s_barrier
	s_setprio 1
	s_waitcnt lgkmcnt(0)
	v_mfma_i32_16x16x64_i8 v[142:145], v[74:77], v[188:191], v[142:145]
	v_mfma_i32_16x16x64_i8 v[138:141], v[90:93], v[188:191], v[138:141]
	v_mfma_i32_16x16x64_i8 v[126:129], v[74:77], v[196:199], v[126:129]
	v_mfma_i32_16x16x64_i8 v[122:125], v[90:93], v[196:199], v[122:125]
	v_mfma_i32_16x16x64_i8 v[110:113], v[74:77], v[204:207], v[110:113]
	v_mfma_i32_16x16x64_i8 v[106:109], v[90:93], v[204:207], v[106:109]
	v_mfma_i32_16x16x64_i8 v[86:89], v[74:77], v[212:215], v[86:89]
	v_mfma_i32_16x16x64_i8 v[82:85], v[90:93], v[212:215], v[82:85]
	v_mfma_i32_16x16x64_i8 v[142:145], v[78:81], v[192:195], v[142:145]
	v_mfma_i32_16x16x64_i8 v[138:141], v[94:97], v[192:195], v[138:141]
	v_mfma_i32_16x16x64_i8 v[126:129], v[78:81], v[200:203], v[126:129]
	v_mfma_i32_16x16x64_i8 v[122:125], v[94:97], v[200:203], v[122:125]
	v_mfma_i32_16x16x64_i8 v[110:113], v[78:81], v[208:211], v[110:113]
	v_mfma_i32_16x16x64_i8 v[106:109], v[94:97], v[208:211], v[106:109]
	v_mfma_i32_16x16x64_i8 v[86:89], v[78:81], v[216:219], v[86:89]
	v_mfma_i32_16x16x64_i8 v[82:85], v[94:97], v[216:219], v[82:85]
	v_mfma_i32_16x16x64_i8 v[134:137], v[164:167], v[188:191], v[134:137]
	v_mfma_i32_16x16x64_i8 v[130:133], v[180:183], v[188:191], v[130:133]
	v_mfma_i32_16x16x64_i8 v[118:121], v[164:167], v[196:199], v[118:121]
	v_mfma_i32_16x16x64_i8 v[114:117], v[180:183], v[196:199], v[114:117]
	v_mfma_i32_16x16x64_i8 v[102:105], v[164:167], v[204:207], v[102:105]
	v_mfma_i32_16x16x64_i8 v[98:101], v[180:183], v[204:207], v[98:101]
	v_mfma_i32_16x16x64_i8 v[70:73], v[164:167], v[212:215], v[70:73]
	v_mfma_i32_16x16x64_i8 v[66:69], v[180:183], v[212:215], v[66:69]
	v_mfma_i32_16x16x64_i8 v[134:137], v[176:179], v[192:195], v[134:137]
	v_mfma_i32_16x16x64_i8 v[130:133], v[184:187], v[192:195], v[130:133]
	v_mfma_i32_16x16x64_i8 v[118:121], v[176:179], v[200:203], v[118:121]
	v_mfma_i32_16x16x64_i8 v[114:117], v[184:187], v[200:203], v[114:117]
	v_mfma_i32_16x16x64_i8 v[102:105], v[176:179], v[208:211], v[102:105]
	v_mfma_i32_16x16x64_i8 v[98:101], v[184:187], v[208:211], v[98:101]
	v_mfma_i32_16x16x64_i8 v[70:73], v[176:179], v[216:219], v[70:73]
	v_mfma_i32_16x16x64_i8 v[66:69], v[184:187], v[216:219], v[66:69]
	s_setprio 0
	s_barrier
	s_add_i32 s52, s62, s13
	v_lshl_add_u64 v[168:169], v[168:169], 0, s[8:9]
	s_mov_b32 m0, s52
	ds_read_b128 v[188:191], v175 offset:49152
	ds_read_b128 v[192:195], v175 offset:50176
	ds_read_b128 v[196:199], v175 offset:51200
	ds_read_b128 v[200:203], v175 offset:52224
	ds_read_b128 v[204:207], v175 offset:53248
	ds_read_b128 v[208:211], v175 offset:54272
	ds_read_b128 v[212:215], v175 offset:55296
	ds_read_b128 v[216:219], v175 offset:56320
	global_load_lds_dwordx4 v[168:169], off
	s_add_i32 m0, s52, 0x2000
	s_add_u32 s50, s50, 0x80080
	v_lshl_add_u64 v[168:169], v[220:221], 0, s[8:9]
	s_addc_u32 s51, s51, 0
	s_add_i32 s52, s63, s13
	global_load_lds_dwordx4 v[168:169], off
	s_mov_b32 m0, s52
	v_lshl_add_u64 v[168:169], s[50:51], 0, v[148:149]
	global_load_lds_dwordx4 v[168:169], off
	s_add_i32 m0, s52, 0x2000
	v_lshl_add_u64 v[168:169], s[50:51], 0, v[152:153]
	global_load_lds_dwordx4 v[168:169], off
	s_mov_b32 m0, s24
	v_lshl_add_u64 v[168:169], v[222:223], 0, s[8:9]
	global_load_lds_dwordx4 v[168:169], off
	s_mov_b32 m0, s25
	v_lshl_add_u64 v[168:169], v[224:225], 0, s[8:9]
	global_load_lds_dwordx4 v[168:169], off
	s_waitcnt vmcnt(8)
	s_waitcnt lgkmcnt(0)
	s_barrier
	s_setprio 1
	s_waitcnt lgkmcnt(0)
	v_mfma_i32_16x16x64_i8 v[62:65], v[74:77], v[188:191], v[62:65]
	v_mfma_i32_16x16x64_i8 v[58:61], v[90:93], v[188:191], v[58:61]
	v_mfma_i32_16x16x64_i8 v[46:49], v[74:77], v[196:199], v[46:49]
	v_mfma_i32_16x16x64_i8 v[42:45], v[90:93], v[196:199], v[42:45]
	v_mfma_i32_16x16x64_i8 v[30:33], v[74:77], v[204:207], v[30:33]
	v_mfma_i32_16x16x64_i8 v[26:29], v[90:93], v[204:207], v[26:29]
	v_mfma_i32_16x16x64_i8 v[14:17], v[74:77], v[212:215], v[14:17]
	v_mfma_i32_16x16x64_i8 v[10:13], v[90:93], v[212:215], v[10:13]
	v_mfma_i32_16x16x64_i8 v[62:65], v[78:81], v[192:195], v[62:65]
	v_mfma_i32_16x16x64_i8 v[58:61], v[94:97], v[192:195], v[58:61]
	v_mfma_i32_16x16x64_i8 v[46:49], v[78:81], v[200:203], v[46:49]
	v_mfma_i32_16x16x64_i8 v[42:45], v[94:97], v[200:203], v[42:45]
	v_mfma_i32_16x16x64_i8 v[30:33], v[78:81], v[208:211], v[30:33]
	v_mfma_i32_16x16x64_i8 v[26:29], v[94:97], v[208:211], v[26:29]
	v_mfma_i32_16x16x64_i8 v[14:17], v[78:81], v[216:219], v[14:17]
	v_mfma_i32_16x16x64_i8 v[10:13], v[94:97], v[216:219], v[10:13]
	v_mfma_i32_16x16x64_i8 v[54:57], v[164:167], v[188:191], v[54:57]
	v_mfma_i32_16x16x64_i8 v[50:53], v[180:183], v[188:191], v[50:53]
	v_mfma_i32_16x16x64_i8 v[38:41], v[164:167], v[196:199], v[38:41]
	v_mfma_i32_16x16x64_i8 v[34:37], v[180:183], v[196:199], v[34:37]
	v_mfma_i32_16x16x64_i8 v[22:25], v[164:167], v[204:207], v[22:25]
	v_mfma_i32_16x16x64_i8 v[18:21], v[180:183], v[204:207], v[18:21]
	v_mfma_i32_16x16x64_i8 v[6:9], v[164:167], v[212:215], v[6:9]
	v_mfma_i32_16x16x64_i8 v[2:5], v[180:183], v[212:215], v[2:5]
	v_mfma_i32_16x16x64_i8 v[54:57], v[176:179], v[192:195], v[54:57]
	v_mfma_i32_16x16x64_i8 v[50:53], v[184:187], v[192:195], v[50:53]
	v_mfma_i32_16x16x64_i8 v[38:41], v[176:179], v[200:203], v[38:41]
	v_mfma_i32_16x16x64_i8 v[34:37], v[184:187], v[200:203], v[34:37]
	v_mfma_i32_16x16x64_i8 v[22:25], v[176:179], v[208:211], v[22:25]
	v_mfma_i32_16x16x64_i8 v[18:21], v[184:187], v[208:211], v[18:21]
	v_mfma_i32_16x16x64_i8 v[6:9], v[176:179], v[216:219], v[6:9]
	v_mfma_i32_16x16x64_i8 v[2:5], v[184:187], v[216:219], v[2:5]
	s_setprio 0
	s_barrier
	s_add_i32 s61, s61, 2
	s_add_u32 s48, s48, 0x100
	s_addc_u32 s49, s49, 0
	s_add_u32 s57, s57, 0x100
	s_addc_u32 s60, s60, 0
	s_cmp_lt_u32 s61, 30
	s_cbranch_scc1 .LBB0_429
	s_nop 0
	s_nop 0
	s_nop 0
	s_nop 0
	s_nop 0
	s_nop 0
	s_nop 0
	s_nop 0
	s_nop 0
	s_nop 0
	s_nop 0
	s_nop 0
	s_nop 0
	s_nop 0
	s_nop 0
	s_nop 0
	s_andn2_b64 vcc, exec, s[10:11]
	s_cbranch_vccz .LBB0_434
	v_lshl_add_u32 v164, s46, 8, v170
	s_cmp_gt_i32 s55, 39
	s_mov_b64 s[46:47], -1
	s_cbranch_scc1 .LBB0_435

.LBB0_449:
	ds_read_b128 v[148:151], v155
	ds_read_b128 v[158:161], v155 offset:1024
	ds_read_b128 v[162:165], v155 offset:2048
	ds_read_b128 v[166:169], v155 offset:3072
	ds_read_b128 v[170:173], v156
	ds_read_b128 v[174:177], v156 offset:1024
	ds_read_b128 v[178:181], v156 offset:2048
	ds_read_b128 v[182:185], v156 offset:3072
	s_add_u32 s50, s48, 0xfff00080
	s_addc_u32 s51, s49, -1
	s_cmp_eq_u32 s57, 60
	s_cselect_b32 s53, s41, s51
	s_cselect_b32 s52, s47, s50
	s_cselect_b32 s51, s39, s56
	s_cselect_b32 s50, s54, s55
	v_lshl_add_u64 v[218:219], s[48:49], 0, v[140:141]
	s_add_i32 m0, s18, 0xc000
	ds_read_b128 v[186:189], v157
	ds_read_b128 v[190:193], v157 offset:1024
	ds_read_b128 v[194:197], v157 offset:2048
	ds_read_b128 v[198:201], v157 offset:3072
	ds_read_b128 v[202:205], v157 offset:4096
	ds_read_b128 v[206:209], v157 offset:5120
	ds_read_b128 v[210:213], v157 offset:6144
	ds_read_b128 v[214:217], v157 offset:7168
	global_load_lds_dwordx4 v[218:219], off
	s_add_i32 m0, s18, 0xe000
	v_lshl_add_u64 v[218:219], s[48:49], 0, v[142:143]
	global_load_lds_dwordx4 v[218:219], off
	s_waitcnt vmcnt(8)
	s_waitcnt lgkmcnt(0)
	s_barrier
	s_setprio 1
	s_waitcnt lgkmcnt(0)
	v_mfma_f32_16x16x32_bf16 v[126:129], v[148:151], v[186:189], v[126:129]
	v_mfma_f32_16x16x32_bf16 v[122:125], v[162:165], v[186:189], v[122:125]
	v_mfma_f32_16x16x32_bf16 v[118:121], v[148:151], v[194:197], v[118:121]
	v_mfma_f32_16x16x32_bf16 v[110:113], v[162:165], v[194:197], v[110:113]
	v_mfma_f32_16x16x32_bf16 v[102:105], v[148:151], v[202:205], v[102:105]
	v_mfma_f32_16x16x32_bf16 v[94:97], v[162:165], v[202:205], v[94:97]
	v_mfma_f32_16x16x32_bf16 v[86:89], v[148:151], v[210:213], v[86:89]
	v_mfma_f32_16x16x32_bf16 v[78:81], v[162:165], v[210:213], v[78:81]
	v_mfma_f32_16x16x32_bf16 v[126:129], v[158:161], v[190:193], v[126:129]
	v_mfma_f32_16x16x32_bf16 v[122:125], v[166:169], v[190:193], v[122:125]
	v_mfma_f32_16x16x32_bf16 v[118:121], v[158:161], v[198:201], v[118:121]
	v_mfma_f32_16x16x32_bf16 v[110:113], v[166:169], v[198:201], v[110:113]
	v_mfma_f32_16x16x32_bf16 v[102:105], v[158:161], v[206:209], v[102:105]
	v_mfma_f32_16x16x32_bf16 v[94:97], v[166:169], v[206:209], v[94:97]
	v_mfma_f32_16x16x32_bf16 v[86:89], v[158:161], v[214:217], v[86:89]
	v_mfma_f32_16x16x32_bf16 v[78:81], v[166:169], v[214:217], v[78:81]
	v_mfma_f32_16x16x32_bf16 v[114:117], v[170:173], v[186:189], v[114:117]
	v_mfma_f32_16x16x32_bf16 v[106:109], v[178:181], v[186:189], v[106:109]
	v_mfma_f32_16x16x32_bf16 v[98:101], v[170:173], v[194:197], v[98:101]
	v_mfma_f32_16x16x32_bf16 v[90:93], v[178:181], v[194:197], v[90:93]
	v_mfma_f32_16x16x32_bf16 v[82:85], v[170:173], v[202:205], v[82:85]
	v_mfma_f32_16x16x32_bf16 v[74:77], v[178:181], v[202:205], v[74:77]
	v_mfma_f32_16x16x32_bf16 v[70:73], v[170:173], v[210:213], v[70:73]
	v_mfma_f32_16x16x32_bf16 v[66:69], v[178:181], v[210:213], v[66:69]
	v_mfma_f32_16x16x32_bf16 v[114:117], v[174:177], v[190:193], v[114:117]
	v_mfma_f32_16x16x32_bf16 v[106:109], v[182:185], v[190:193], v[106:109]
	v_mfma_f32_16x16x32_bf16 v[98:101], v[174:177], v[198:201], v[98:101]
	v_mfma_f32_16x16x32_bf16 v[90:93], v[182:185], v[198:201], v[90:93]
	v_mfma_f32_16x16x32_bf16 v[82:85], v[174:177], v[206:209], v[82:85]
	v_mfma_f32_16x16x32_bf16 v[74:77], v[182:185], v[206:209], v[74:77]
	v_mfma_f32_16x16x32_bf16 v[70:73], v[174:177], v[214:217], v[70:73]
	v_mfma_f32_16x16x32_bf16 v[66:69], v[182:185], v[214:217], v[66:69]
	s_setprio 0
	s_barrier
	s_add_i32 s60, s33, s16
	v_lshl_add_u64 v[218:219], s[50:51], 0, v[134:135]
	s_mov_b32 m0, s60
	ds_read_b128 v[186:189], v157 offset:16384
	ds_read_b128 v[190:193], v157 offset:17408
	ds_read_b128 v[194:197], v157 offset:18432
	ds_read_b128 v[198:201], v157 offset:19456
	ds_read_b128 v[202:205], v157 offset:20480
	ds_read_b128 v[206:209], v157 offset:21504
	ds_read_b128 v[210:213], v157 offset:22528
	ds_read_b128 v[214:217], v157 offset:23552
	global_load_lds_dwordx4 v[218:219], off
	s_add_i32 m0, s60, 0x2000
	s_add_u32 s60, s50, 0x100000
	v_lshl_add_u64 v[220:221], s[50:51], 0, v[130:131]
	s_addc_u32 s61, s51, 0
	s_add_i32 s62, s34, s16
	global_load_lds_dwordx4 v[220:221], off
	v_lshl_add_u64 v[222:223], s[60:61], 0, v[134:135]
	s_mov_b32 m0, s62
	v_lshl_add_u64 v[224:225], s[52:53], 0, v[132:133]
	global_load_lds_dwordx4 v[222:223], off
	s_add_i32 m0, s62, 0x2000
	v_lshl_add_u64 v[222:223], s[60:61], 0, v[130:131]
	global_load_lds_dwordx4 v[222:223], off
	s_mov_b32 m0, s18
	v_lshl_add_u64 v[222:223], s[52:53], 0, v[136:137]
	global_load_lds_dwordx4 v[222:223], off
	s_mov_b32 m0, s19
	s_nop 0
	global_load_lds_dwordx4 v[224:225], off
	s_waitcnt vmcnt(8)
	s_waitcnt lgkmcnt(0)
	s_barrier
	s_setprio 1
	s_waitcnt lgkmcnt(0)
	v_mfma_f32_16x16x32_bf16 v[62:65], v[148:151], v[186:189], v[62:65]
	v_mfma_f32_16x16x32_bf16 v[58:61], v[162:165], v[186:189], v[58:61]
	v_mfma_f32_16x16x32_bf16 v[54:57], v[148:151], v[194:197], v[54:57]
	v_mfma_f32_16x16x32_bf16 v[46:49], v[162:165], v[194:197], v[46:49]
	v_mfma_f32_16x16x32_bf16 v[38:41], v[148:151], v[202:205], v[38:41]
	v_mfma_f32_16x16x32_bf16 v[30:33], v[162:165], v[202:205], v[30:33]
	v_mfma_f32_16x16x32_bf16 v[22:25], v[148:151], v[210:213], v[22:25]
	v_mfma_f32_16x16x32_bf16 v[14:17], v[162:165], v[210:213], v[14:17]
	v_mfma_f32_16x16x32_bf16 v[62:65], v[158:161], v[190:193], v[62:65]
	v_mfma_f32_16x16x32_bf16 v[58:61], v[166:169], v[190:193], v[58:61]
	v_mfma_f32_16x16x32_bf16 v[54:57], v[158:161], v[198:201], v[54:57]
	v_mfma_f32_16x16x32_bf16 v[46:49], v[166:169], v[198:201], v[46:49]
	v_mfma_f32_16x16x32_bf16 v[38:41], v[158:161], v[206:209], v[38:41]
	v_mfma_f32_16x16x32_bf16 v[30:33], v[166:169], v[206:209], v[30:33]
	v_mfma_f32_16x16x32_bf16 v[22:25], v[158:161], v[214:217], v[22:25]
	v_mfma_f32_16x16x32_bf16 v[14:17], v[166:169], v[214:217], v[14:17]
	v_mfma_f32_16x16x32_bf16 v[50:53], v[170:173], v[186:189], v[50:53]
	v_mfma_f32_16x16x32_bf16 v[42:45], v[178:181], v[186:189], v[42:45]
	v_mfma_f32_16x16x32_bf16 v[34:37], v[170:173], v[194:197], v[34:37]
	v_mfma_f32_16x16x32_bf16 v[26:29], v[178:181], v[194:197], v[26:29]
	v_mfma_f32_16x16x32_bf16 v[18:21], v[170:173], v[202:205], v[18:21]
	v_mfma_f32_16x16x32_bf16 v[10:13], v[178:181], v[202:205], v[10:13]
	v_mfma_f32_16x16x32_bf16 v[6:9], v[170:173], v[210:213], v[6:9]
	v_mfma_f32_16x16x32_bf16 v[2:5], v[178:181], v[210:213], v[2:5]
	v_mfma_f32_16x16x32_bf16 v[50:53], v[174:177], v[190:193], v[50:53]
	v_mfma_f32_16x16x32_bf16 v[42:45], v[182:185], v[190:193], v[42:45]
	v_mfma_f32_16x16x32_bf16 v[34:37], v[174:177], v[198:201], v[34:37]
	v_mfma_f32_16x16x32_bf16 v[26:29], v[182:185], v[198:201], v[26:29]
	v_mfma_f32_16x16x32_bf16 v[18:21], v[174:177], v[206:209], v[18:21]
	v_mfma_f32_16x16x32_bf16 v[10:13], v[182:185], v[206:209], v[10:13]
	v_mfma_f32_16x16x32_bf16 v[6:9], v[174:177], v[214:217], v[6:9]
	v_mfma_f32_16x16x32_bf16 v[2:5], v[182:185], v[214:217], v[2:5]
	s_setprio 0
	s_barrier
	s_add_i32 s60, 0, 0x18000
	s_add_i32 s61, 0, 0x1c000
	v_add_u32_e32 v166, s60, v153
	v_add_u32_e32 v182, s61, v153
	ds_read_b128 v[148:151], v166
	ds_read_b128 v[158:161], v166 offset:1024
	ds_read_b128 v[162:165], v166 offset:2048
	ds_read_b128 v[166:169], v166 offset:3072
	ds_read_b128 v[170:173], v182
	ds_read_b128 v[174:177], v182 offset:1024
	ds_read_b128 v[178:181], v182 offset:2048
	ds_read_b128 v[182:185], v182 offset:3072
	s_add_u32 s52, s52, 0x100000
	s_addc_u32 s53, s53, 0
	s_mov_b32 m0, s20
	v_lshl_add_u64 v[226:227], s[52:53], 0, v[136:137]
	ds_read_b128 v[186:189], v157 offset:32768
	ds_read_b128 v[190:193], v157 offset:33792
	ds_read_b128 v[194:197], v157 offset:34816
	ds_read_b128 v[198:201], v157 offset:35840
	ds_read_b128 v[202:205], v157 offset:36864
	ds_read_b128 v[206:209], v157 offset:37888
	ds_read_b128 v[210:213], v157 offset:38912
	ds_read_b128 v[214:217], v157 offset:39936
	global_load_lds_dwordx4 v[226:227], off
	s_mov_b32 m0, s21
	v_lshl_add_u64 v[226:227], s[52:53], 0, v[132:133]
	global_load_lds_dwordx4 v[226:227], off
	s_waitcnt vmcnt(8)
	s_waitcnt lgkmcnt(0)
	s_barrier
	s_setprio 1
	s_waitcnt lgkmcnt(0)
	v_mfma_f32_16x16x32_bf16 v[126:129], v[148:151], v[186:189], v[126:129]
	v_mfma_f32_16x16x32_bf16 v[122:125], v[162:165], v[186:189], v[122:125]
	v_mfma_f32_16x16x32_bf16 v[118:121], v[148:151], v[194:197], v[118:121]
	v_mfma_f32_16x16x32_bf16 v[110:113], v[162:165], v[194:197], v[110:113]
	v_mfma_f32_16x16x32_bf16 v[102:105], v[148:151], v[202:205], v[102:105]
	v_mfma_f32_16x16x32_bf16 v[94:97], v[162:165], v[202:205], v[94:97]
	v_mfma_f32_16x16x32_bf16 v[86:89], v[148:151], v[210:213], v[86:89]
	v_mfma_f32_16x16x32_bf16 v[78:81], v[162:165], v[210:213], v[78:81]
	v_mfma_f32_16x16x32_bf16 v[126:129], v[158:161], v[190:193], v[126:129]
	v_mfma_f32_16x16x32_bf16 v[122:125], v[166:169], v[190:193], v[122:125]
	v_mfma_f32_16x16x32_bf16 v[118:121], v[158:161], v[198:201], v[118:121]
	v_mfma_f32_16x16x32_bf16 v[110:113], v[166:169], v[198:201], v[110:113]
	v_mfma_f32_16x16x32_bf16 v[102:105], v[158:161], v[206:209], v[102:105]
	v_mfma_f32_16x16x32_bf16 v[94:97], v[166:169], v[206:209], v[94:97]
	v_mfma_f32_16x16x32_bf16 v[86:89], v[158:161], v[214:217], v[86:89]
	v_mfma_f32_16x16x32_bf16 v[78:81], v[166:169], v[214:217], v[78:81]
	v_mfma_f32_16x16x32_bf16 v[114:117], v[170:173], v[186:189], v[114:117]
	v_mfma_f32_16x16x32_bf16 v[106:109], v[178:181], v[186:189], v[106:109]
	v_mfma_f32_16x16x32_bf16 v[98:101], v[170:173], v[194:197], v[98:101]
	v_mfma_f32_16x16x32_bf16 v[90:93], v[178:181], v[194:197], v[90:93]
	v_mfma_f32_16x16x32_bf16 v[82:85], v[170:173], v[202:205], v[82:85]
	v_mfma_f32_16x16x32_bf16 v[74:77], v[178:181], v[202:205], v[74:77]
	v_mfma_f32_16x16x32_bf16 v[70:73], v[170:173], v[210:213], v[70:73]
	v_mfma_f32_16x16x32_bf16 v[66:69], v[178:181], v[210:213], v[66:69]
	v_mfma_f32_16x16x32_bf16 v[114:117], v[174:177], v[190:193], v[114:117]
	v_mfma_f32_16x16x32_bf16 v[106:109], v[182:185], v[190:193], v[106:109]
	v_mfma_f32_16x16x32_bf16 v[98:101], v[174:177], v[198:201], v[98:101]
	v_mfma_f32_16x16x32_bf16 v[90:93], v[182:185], v[198:201], v[90:93]
	v_mfma_f32_16x16x32_bf16 v[82:85], v[174:177], v[206:209], v[82:85]
	v_mfma_f32_16x16x32_bf16 v[74:77], v[182:185], v[206:209], v[74:77]
	v_mfma_f32_16x16x32_bf16 v[70:73], v[174:177], v[214:217], v[70:73]
	v_mfma_f32_16x16x32_bf16 v[66:69], v[182:185], v[214:217], v[66:69]
	s_setprio 0
	s_barrier
	s_add_i32 s52, s60, s16
	v_lshl_add_u64 v[218:219], v[218:219], 0, s[28:29]
	s_mov_b32 m0, s52
	ds_read_b128 v[186:189], v157 offset:49152
	ds_read_b128 v[190:193], v157 offset:50176
	ds_read_b128 v[194:197], v157 offset:51200
	ds_read_b128 v[198:201], v157 offset:52224
	ds_read_b128 v[202:205], v157 offset:53248
	ds_read_b128 v[206:209], v157 offset:54272
	ds_read_b128 v[210:213], v157 offset:55296
	ds_read_b128 v[214:217], v157 offset:56320
	global_load_lds_dwordx4 v[218:219], off
	s_add_i32 m0, s52, 0x2000
	s_add_u32 s50, s50, 0x100080
	v_lshl_add_u64 v[218:219], v[220:221], 0, s[28:29]
	s_addc_u32 s51, s51, 0
	s_add_i32 s52, s61, s16
	global_load_lds_dwordx4 v[218:219], off
	s_mov_b32 m0, s52
	v_lshl_add_u64 v[218:219], s[50:51], 0, v[134:135]
	global_load_lds_dwordx4 v[218:219], off
	s_add_i32 m0, s52, 0x2000
	v_lshl_add_u64 v[218:219], s[50:51], 0, v[130:131]
	global_load_lds_dwordx4 v[218:219], off
	s_mov_b32 m0, s23
	v_lshl_add_u64 v[218:219], v[222:223], 0, s[28:29]
	global_load_lds_dwordx4 v[218:219], off
	s_mov_b32 m0, s24
	v_lshl_add_u64 v[218:219], v[224:225], 0, s[28:29]
	global_load_lds_dwordx4 v[218:219], off
	s_waitcnt vmcnt(8)
	s_waitcnt lgkmcnt(0)
	s_barrier
	s_setprio 1
	s_waitcnt lgkmcnt(0)
	v_mfma_f32_16x16x32_bf16 v[62:65], v[148:151], v[186:189], v[62:65]
	v_mfma_f32_16x16x32_bf16 v[58:61], v[162:165], v[186:189], v[58:61]
	v_mfma_f32_16x16x32_bf16 v[54:57], v[148:151], v[194:197], v[54:57]
	v_mfma_f32_16x16x32_bf16 v[46:49], v[162:165], v[194:197], v[46:49]
	v_mfma_f32_16x16x32_bf16 v[38:41], v[148:151], v[202:205], v[38:41]
	v_mfma_f32_16x16x32_bf16 v[30:33], v[162:165], v[202:205], v[30:33]
	v_mfma_f32_16x16x32_bf16 v[22:25], v[148:151], v[210:213], v[22:25]
	v_mfma_f32_16x16x32_bf16 v[14:17], v[162:165], v[210:213], v[14:17]
	v_mfma_f32_16x16x32_bf16 v[62:65], v[158:161], v[190:193], v[62:65]
	v_mfma_f32_16x16x32_bf16 v[58:61], v[166:169], v[190:193], v[58:61]
	v_mfma_f32_16x16x32_bf16 v[54:57], v[158:161], v[198:201], v[54:57]
	v_mfma_f32_16x16x32_bf16 v[46:49], v[166:169], v[198:201], v[46:49]
	v_mfma_f32_16x16x32_bf16 v[38:41], v[158:161], v[206:209], v[38:41]
	v_mfma_f32_16x16x32_bf16 v[30:33], v[166:169], v[206:209], v[30:33]
	v_mfma_f32_16x16x32_bf16 v[22:25], v[158:161], v[214:217], v[22:25]
	v_mfma_f32_16x16x32_bf16 v[14:17], v[166:169], v[214:217], v[14:17]
	v_mfma_f32_16x16x32_bf16 v[50:53], v[170:173], v[186:189], v[50:53]
	v_mfma_f32_16x16x32_bf16 v[42:45], v[178:181], v[186:189], v[42:45]
	v_mfma_f32_16x16x32_bf16 v[34:37], v[170:173], v[194:197], v[34:37]
	v_mfma_f32_16x16x32_bf16 v[26:29], v[178:181], v[194:197], v[26:29]
	v_mfma_f32_16x16x32_bf16 v[18:21], v[170:173], v[202:205], v[18:21]
	v_mfma_f32_16x16x32_bf16 v[10:13], v[178:181], v[202:205], v[10:13]
	v_mfma_f32_16x16x32_bf16 v[6:9], v[170:173], v[210:213], v[6:9]
	v_mfma_f32_16x16x32_bf16 v[2:5], v[178:181], v[210:213], v[2:5]
	v_mfma_f32_16x16x32_bf16 v[50:53], v[174:177], v[190:193], v[50:53]
	v_mfma_f32_16x16x32_bf16 v[42:45], v[182:185], v[190:193], v[42:45]
	v_mfma_f32_16x16x32_bf16 v[34:37], v[174:177], v[198:201], v[34:37]
	v_mfma_f32_16x16x32_bf16 v[26:29], v[182:185], v[198:201], v[26:29]
	v_mfma_f32_16x16x32_bf16 v[18:21], v[174:177], v[206:209], v[18:21]
	v_mfma_f32_16x16x32_bf16 v[10:13], v[182:185], v[206:209], v[10:13]
	v_mfma_f32_16x16x32_bf16 v[6:9], v[174:177], v[214:217], v[6:9]
	v_mfma_f32_16x16x32_bf16 v[2:5], v[182:185], v[214:217], v[2:5]
	s_setprio 0
	s_barrier
	s_add_i32 s57, s57, 2
	s_add_u32 s48, s48, 0x100
	s_addc_u32 s49, s49, 0
	s_add_u32 s55, s55, 0x100
	s_addc_u32 s56, s56, 0
	s_cmp_lt_u32 s57, 62
	s_cbranch_scc1 .LBB0_449
	s_nop 0
	s_nop 0
	s_nop 0
	s_nop 0
	s_nop 0
	s_nop 0
	s_nop 0
	s_nop 0
	s_nop 0
	s_nop 0
	s_nop 0
	s_nop 0
	s_nop 0
	s_nop 0
	s_nop 0
	s_nop 0
	s_andn2_b64 vcc, exec, s[30:31]
	s_cbranch_vccz .LBB0_454
	v_lshl_add_u32 v148, s46, 8, v152
	s_cmp_gt_i32 s35, 63
	s_mov_b64 s[46:47], -1
	s_cbranch_scc1 .LBB0_455

.LBB0_1007:
	ds_read_b128 v[122:125], v161
	ds_read_b128 v[126:129], v161 offset:1024
	ds_read_b128 v[138:141], v161 offset:2048
	ds_read_b128 v[164:167], v161 offset:3072
	ds_read_b128 v[168:171], v162
	ds_read_b128 v[172:175], v162 offset:1024
	ds_read_b128 v[176:179], v162 offset:2048
	ds_read_b128 v[180:183], v162 offset:3072
	s_add_u32 s26, s24, 0xfff00080
	s_addc_u32 s27, s25, -1
	s_cmp_eq_u32 s50, 60
	s_cselect_b32 s29, s17, s27
	s_cselect_b32 s28, s46, s26
	s_cselect_b32 s27, s15, s49
	s_cselect_b32 s26, s47, s48
	v_lshl_add_u64 v[216:217], s[24:25], 0, v[150:151]
	s_add_i32 m0, s34, 0xc000
	ds_read_b128 v[184:187], v163
	ds_read_b128 v[188:191], v163 offset:1024
	ds_read_b128 v[192:195], v163 offset:2048
	ds_read_b128 v[196:199], v163 offset:3072
	ds_read_b128 v[200:203], v163 offset:4096
	ds_read_b128 v[204:207], v163 offset:5120
	ds_read_b128 v[208:211], v163 offset:6144
	ds_read_b128 v[212:215], v163 offset:7168
	global_load_lds_dwordx4 v[216:217], off
	s_add_i32 m0, s34, 0xe000
	v_lshl_add_u64 v[216:217], s[24:25], 0, v[152:153]
	global_load_lds_dwordx4 v[216:217], off
	s_waitcnt vmcnt(8)
	s_waitcnt lgkmcnt(0)
	s_barrier
	s_setprio 1
	s_waitcnt lgkmcnt(0)
	v_mfma_f32_16x16x32_bf16 v[134:137], v[122:125], v[184:187], v[134:137]
	v_mfma_f32_16x16x32_bf16 v[130:133], v[138:141], v[184:187], v[130:133]
	v_mfma_f32_16x16x32_bf16 v[110:113], v[122:125], v[192:195], v[110:113]
	v_mfma_f32_16x16x32_bf16 v[106:109], v[138:141], v[192:195], v[106:109]
	v_mfma_f32_16x16x32_bf16 v[94:97], v[122:125], v[200:203], v[94:97]
	v_mfma_f32_16x16x32_bf16 v[90:93], v[138:141], v[200:203], v[90:93]
	v_mfma_f32_16x16x32_bf16 v[78:81], v[122:125], v[208:211], v[78:81]
	v_mfma_f32_16x16x32_bf16 v[74:77], v[138:141], v[208:211], v[74:77]
	v_mfma_f32_16x16x32_bf16 v[134:137], v[126:129], v[188:191], v[134:137]
	v_mfma_f32_16x16x32_bf16 v[130:133], v[164:167], v[188:191], v[130:133]
	v_mfma_f32_16x16x32_bf16 v[110:113], v[126:129], v[196:199], v[110:113]
	v_mfma_f32_16x16x32_bf16 v[106:109], v[164:167], v[196:199], v[106:109]
	v_mfma_f32_16x16x32_bf16 v[94:97], v[126:129], v[204:207], v[94:97]
	v_mfma_f32_16x16x32_bf16 v[90:93], v[164:167], v[204:207], v[90:93]
	v_mfma_f32_16x16x32_bf16 v[78:81], v[126:129], v[212:215], v[78:81]
	v_mfma_f32_16x16x32_bf16 v[74:77], v[164:167], v[212:215], v[74:77]
	v_mfma_f32_16x16x32_bf16 v[118:121], v[168:171], v[184:187], v[118:121]
	v_mfma_f32_16x16x32_bf16 v[114:117], v[176:179], v[184:187], v[114:117]
	v_mfma_f32_16x16x32_bf16 v[102:105], v[168:171], v[192:195], v[102:105]
	v_mfma_f32_16x16x32_bf16 v[98:101], v[176:179], v[192:195], v[98:101]
	v_mfma_f32_16x16x32_bf16 v[86:89], v[168:171], v[200:203], v[86:89]
	v_mfma_f32_16x16x32_bf16 v[82:85], v[176:179], v[200:203], v[82:85]
	v_mfma_f32_16x16x32_bf16 v[70:73], v[168:171], v[208:211], v[70:73]
	v_mfma_f32_16x16x32_bf16 v[66:69], v[176:179], v[208:211], v[66:69]
	v_mfma_f32_16x16x32_bf16 v[118:121], v[172:175], v[188:191], v[118:121]
	v_mfma_f32_16x16x32_bf16 v[114:117], v[180:183], v[188:191], v[114:117]
	v_mfma_f32_16x16x32_bf16 v[102:105], v[172:175], v[196:199], v[102:105]
	v_mfma_f32_16x16x32_bf16 v[98:101], v[180:183], v[196:199], v[98:101]
	v_mfma_f32_16x16x32_bf16 v[86:89], v[172:175], v[204:207], v[86:89]
	v_mfma_f32_16x16x32_bf16 v[82:85], v[180:183], v[204:207], v[82:85]
	v_mfma_f32_16x16x32_bf16 v[70:73], v[172:175], v[212:215], v[70:73]
	v_mfma_f32_16x16x32_bf16 v[66:69], v[180:183], v[212:215], v[66:69]
	s_setprio 0
	s_barrier
	s_add_i32 s51, s44, s33
	v_lshl_add_u64 v[216:217], s[26:27], 0, v[146:147]
	s_mov_b32 m0, s51
	ds_read_b128 v[184:187], v163 offset:16384
	ds_read_b128 v[188:191], v163 offset:17408
	ds_read_b128 v[192:195], v163 offset:18432
	ds_read_b128 v[196:199], v163 offset:19456
	ds_read_b128 v[200:203], v163 offset:20480
	ds_read_b128 v[204:207], v163 offset:21504
	ds_read_b128 v[208:211], v163 offset:22528
	ds_read_b128 v[212:215], v163 offset:23552
	global_load_lds_dwordx4 v[216:217], off
	s_add_i32 m0, s51, 0x2000
	s_add_u32 s52, s26, 0x100000
	v_lshl_add_u64 v[218:219], s[26:27], 0, v[142:143]
	s_addc_u32 s53, s27, 0
	s_add_i32 s51, s45, s33
	global_load_lds_dwordx4 v[218:219], off
	v_lshl_add_u64 v[220:221], s[52:53], 0, v[146:147]
	s_mov_b32 m0, s51
	v_lshl_add_u64 v[222:223], s[28:29], 0, v[144:145]
	global_load_lds_dwordx4 v[220:221], off
	s_add_i32 m0, s51, 0x2000
	v_lshl_add_u64 v[220:221], s[52:53], 0, v[142:143]
	global_load_lds_dwordx4 v[220:221], off
	s_mov_b32 m0, s34
	v_lshl_add_u64 v[220:221], s[28:29], 0, v[148:149]
	global_load_lds_dwordx4 v[220:221], off
	s_mov_b32 m0, s35
	s_nop 0
	global_load_lds_dwordx4 v[222:223], off
	s_waitcnt vmcnt(8)
	s_waitcnt lgkmcnt(0)
	s_barrier
	s_setprio 1
	s_waitcnt lgkmcnt(0)
	v_mfma_f32_16x16x32_bf16 v[62:65], v[122:125], v[184:187], v[62:65]
	v_mfma_f32_16x16x32_bf16 v[58:61], v[138:141], v[184:187], v[58:61]
	v_mfma_f32_16x16x32_bf16 v[46:49], v[122:125], v[192:195], v[46:49]
	v_mfma_f32_16x16x32_bf16 v[42:45], v[138:141], v[192:195], v[42:45]
	v_mfma_f32_16x16x32_bf16 v[30:33], v[122:125], v[200:203], v[30:33]
	v_mfma_f32_16x16x32_bf16 v[26:29], v[138:141], v[200:203], v[26:29]
	v_mfma_f32_16x16x32_bf16 v[14:17], v[122:125], v[208:211], v[14:17]
	v_mfma_f32_16x16x32_bf16 v[10:13], v[138:141], v[208:211], v[10:13]
	v_mfma_f32_16x16x32_bf16 v[62:65], v[126:129], v[188:191], v[62:65]
	v_mfma_f32_16x16x32_bf16 v[58:61], v[164:167], v[188:191], v[58:61]
	v_mfma_f32_16x16x32_bf16 v[46:49], v[126:129], v[196:199], v[46:49]
	v_mfma_f32_16x16x32_bf16 v[42:45], v[164:167], v[196:199], v[42:45]
	v_mfma_f32_16x16x32_bf16 v[30:33], v[126:129], v[204:207], v[30:33]
	v_mfma_f32_16x16x32_bf16 v[26:29], v[164:167], v[204:207], v[26:29]
	v_mfma_f32_16x16x32_bf16 v[14:17], v[126:129], v[212:215], v[14:17]
	v_mfma_f32_16x16x32_bf16 v[10:13], v[164:167], v[212:215], v[10:13]
	v_mfma_f32_16x16x32_bf16 v[54:57], v[168:171], v[184:187], v[54:57]
	v_mfma_f32_16x16x32_bf16 v[50:53], v[176:179], v[184:187], v[50:53]
	v_mfma_f32_16x16x32_bf16 v[38:41], v[168:171], v[192:195], v[38:41]
	v_mfma_f32_16x16x32_bf16 v[34:37], v[176:179], v[192:195], v[34:37]
	v_mfma_f32_16x16x32_bf16 v[22:25], v[168:171], v[200:203], v[22:25]
	v_mfma_f32_16x16x32_bf16 v[18:21], v[176:179], v[200:203], v[18:21]
	v_mfma_f32_16x16x32_bf16 v[6:9], v[168:171], v[208:211], v[6:9]
	v_mfma_f32_16x16x32_bf16 v[2:5], v[176:179], v[208:211], v[2:5]
	v_mfma_f32_16x16x32_bf16 v[54:57], v[172:175], v[188:191], v[54:57]
	v_mfma_f32_16x16x32_bf16 v[50:53], v[180:183], v[188:191], v[50:53]
	v_mfma_f32_16x16x32_bf16 v[38:41], v[172:175], v[196:199], v[38:41]
	v_mfma_f32_16x16x32_bf16 v[34:37], v[180:183], v[196:199], v[34:37]
	v_mfma_f32_16x16x32_bf16 v[22:25], v[172:175], v[204:207], v[22:25]
	v_mfma_f32_16x16x32_bf16 v[18:21], v[180:183], v[204:207], v[18:21]
	v_mfma_f32_16x16x32_bf16 v[6:9], v[172:175], v[212:215], v[6:9]
	v_mfma_f32_16x16x32_bf16 v[2:5], v[180:183], v[212:215], v[2:5]
	s_setprio 0
	s_barrier
	s_add_i32 s51, 0, 0x18000
	s_add_i32 s52, 0, 0x1c000
	v_add_u32_e32 v164, s51, v159
	v_add_u32_e32 v180, s52, v159
	ds_read_b128 v[122:125], v164
	ds_read_b128 v[126:129], v164 offset:1024
	ds_read_b128 v[138:141], v164 offset:2048
	ds_read_b128 v[164:167], v164 offset:3072
	ds_read_b128 v[168:171], v180
	ds_read_b128 v[172:175], v180 offset:1024
	ds_read_b128 v[176:179], v180 offset:2048
	ds_read_b128 v[180:183], v180 offset:3072
	s_add_u32 s28, s28, 0x100000
	s_addc_u32 s29, s29, 0
	s_mov_b32 m0, s36
	v_lshl_add_u64 v[224:225], s[28:29], 0, v[148:149]
	ds_read_b128 v[184:187], v163 offset:32768
	ds_read_b128 v[188:191], v163 offset:33792
	ds_read_b128 v[192:195], v163 offset:34816
	ds_read_b128 v[196:199], v163 offset:35840
	ds_read_b128 v[200:203], v163 offset:36864
	ds_read_b128 v[204:207], v163 offset:37888
	ds_read_b128 v[208:211], v163 offset:38912
	ds_read_b128 v[212:215], v163 offset:39936
	global_load_lds_dwordx4 v[224:225], off
	s_mov_b32 m0, s37
	v_lshl_add_u64 v[224:225], s[28:29], 0, v[144:145]
	global_load_lds_dwordx4 v[224:225], off
	s_waitcnt vmcnt(8)
	s_waitcnt lgkmcnt(0)
	s_barrier
	s_setprio 1
	s_waitcnt lgkmcnt(0)
	v_mfma_f32_16x16x32_bf16 v[134:137], v[122:125], v[184:187], v[134:137]
	v_mfma_f32_16x16x32_bf16 v[130:133], v[138:141], v[184:187], v[130:133]
	v_mfma_f32_16x16x32_bf16 v[110:113], v[122:125], v[192:195], v[110:113]
	v_mfma_f32_16x16x32_bf16 v[106:109], v[138:141], v[192:195], v[106:109]
	v_mfma_f32_16x16x32_bf16 v[94:97], v[122:125], v[200:203], v[94:97]
	v_mfma_f32_16x16x32_bf16 v[90:93], v[138:141], v[200:203], v[90:93]
	v_mfma_f32_16x16x32_bf16 v[78:81], v[122:125], v[208:211], v[78:81]
	v_mfma_f32_16x16x32_bf16 v[74:77], v[138:141], v[208:211], v[74:77]
	v_mfma_f32_16x16x32_bf16 v[134:137], v[126:129], v[188:191], v[134:137]
	v_mfma_f32_16x16x32_bf16 v[130:133], v[164:167], v[188:191], v[130:133]
	v_mfma_f32_16x16x32_bf16 v[110:113], v[126:129], v[196:199], v[110:113]
	v_mfma_f32_16x16x32_bf16 v[106:109], v[164:167], v[196:199], v[106:109]
	v_mfma_f32_16x16x32_bf16 v[94:97], v[126:129], v[204:207], v[94:97]
	v_mfma_f32_16x16x32_bf16 v[90:93], v[164:167], v[204:207], v[90:93]
	v_mfma_f32_16x16x32_bf16 v[78:81], v[126:129], v[212:215], v[78:81]
	v_mfma_f32_16x16x32_bf16 v[74:77], v[164:167], v[212:215], v[74:77]
	v_mfma_f32_16x16x32_bf16 v[118:121], v[168:171], v[184:187], v[118:121]
	v_mfma_f32_16x16x32_bf16 v[114:117], v[176:179], v[184:187], v[114:117]
	v_mfma_f32_16x16x32_bf16 v[102:105], v[168:171], v[192:195], v[102:105]
	v_mfma_f32_16x16x32_bf16 v[98:101], v[176:179], v[192:195], v[98:101]
	v_mfma_f32_16x16x32_bf16 v[86:89], v[168:171], v[200:203], v[86:89]
	v_mfma_f32_16x16x32_bf16 v[82:85], v[176:179], v[200:203], v[82:85]
	v_mfma_f32_16x16x32_bf16 v[70:73], v[168:171], v[208:211], v[70:73]
	v_mfma_f32_16x16x32_bf16 v[66:69], v[176:179], v[208:211], v[66:69]
	v_mfma_f32_16x16x32_bf16 v[118:121], v[172:175], v[188:191], v[118:121]
	v_mfma_f32_16x16x32_bf16 v[114:117], v[180:183], v[188:191], v[114:117]
	v_mfma_f32_16x16x32_bf16 v[102:105], v[172:175], v[196:199], v[102:105]
	v_mfma_f32_16x16x32_bf16 v[98:101], v[180:183], v[196:199], v[98:101]
	v_mfma_f32_16x16x32_bf16 v[86:89], v[172:175], v[204:207], v[86:89]
	v_mfma_f32_16x16x32_bf16 v[82:85], v[180:183], v[204:207], v[82:85]
	v_mfma_f32_16x16x32_bf16 v[70:73], v[172:175], v[212:215], v[70:73]
	v_mfma_f32_16x16x32_bf16 v[66:69], v[180:183], v[212:215], v[66:69]
	s_setprio 0
	s_barrier
	s_add_i32 s28, s51, s33
	v_lshl_add_u64 v[216:217], v[216:217], 0, s[10:11]
	s_mov_b32 m0, s28
	ds_read_b128 v[184:187], v163 offset:49152
	ds_read_b128 v[188:191], v163 offset:50176
	ds_read_b128 v[192:195], v163 offset:51200
	ds_read_b128 v[196:199], v163 offset:52224
	ds_read_b128 v[200:203], v163 offset:53248
	ds_read_b128 v[204:207], v163 offset:54272
	ds_read_b128 v[208:211], v163 offset:55296
	ds_read_b128 v[212:215], v163 offset:56320
	global_load_lds_dwordx4 v[216:217], off
	s_add_i32 m0, s28, 0x2000
	s_add_u32 s26, s26, 0x100080
	v_lshl_add_u64 v[216:217], v[218:219], 0, s[10:11]
	s_addc_u32 s27, s27, 0
	s_add_i32 s28, s52, s33
	global_load_lds_dwordx4 v[216:217], off
	s_mov_b32 m0, s28
	v_lshl_add_u64 v[216:217], s[26:27], 0, v[146:147]
	global_load_lds_dwordx4 v[216:217], off
	s_add_i32 m0, s28, 0x2000
	v_lshl_add_u64 v[216:217], s[26:27], 0, v[142:143]
	global_load_lds_dwordx4 v[216:217], off
	s_mov_b32 m0, s41
	v_lshl_add_u64 v[216:217], v[220:221], 0, s[10:11]
	global_load_lds_dwordx4 v[216:217], off
	s_mov_b32 m0, s42
	v_lshl_add_u64 v[216:217], v[222:223], 0, s[10:11]
	global_load_lds_dwordx4 v[216:217], off
	s_waitcnt vmcnt(8)
	s_waitcnt lgkmcnt(0)
	s_barrier
	s_setprio 1
	s_waitcnt lgkmcnt(0)
	v_mfma_f32_16x16x32_bf16 v[62:65], v[122:125], v[184:187], v[62:65]
	v_mfma_f32_16x16x32_bf16 v[58:61], v[138:141], v[184:187], v[58:61]
	v_mfma_f32_16x16x32_bf16 v[46:49], v[122:125], v[192:195], v[46:49]
	v_mfma_f32_16x16x32_bf16 v[42:45], v[138:141], v[192:195], v[42:45]
	v_mfma_f32_16x16x32_bf16 v[30:33], v[122:125], v[200:203], v[30:33]
	v_mfma_f32_16x16x32_bf16 v[26:29], v[138:141], v[200:203], v[26:29]
	v_mfma_f32_16x16x32_bf16 v[14:17], v[122:125], v[208:211], v[14:17]
	v_mfma_f32_16x16x32_bf16 v[10:13], v[138:141], v[208:211], v[10:13]
	v_mfma_f32_16x16x32_bf16 v[62:65], v[126:129], v[188:191], v[62:65]
	v_mfma_f32_16x16x32_bf16 v[58:61], v[164:167], v[188:191], v[58:61]
	v_mfma_f32_16x16x32_bf16 v[46:49], v[126:129], v[196:199], v[46:49]
	v_mfma_f32_16x16x32_bf16 v[42:45], v[164:167], v[196:199], v[42:45]
	v_mfma_f32_16x16x32_bf16 v[30:33], v[126:129], v[204:207], v[30:33]
	v_mfma_f32_16x16x32_bf16 v[26:29], v[164:167], v[204:207], v[26:29]
	v_mfma_f32_16x16x32_bf16 v[14:17], v[126:129], v[212:215], v[14:17]
	v_mfma_f32_16x16x32_bf16 v[10:13], v[164:167], v[212:215], v[10:13]
	v_mfma_f32_16x16x32_bf16 v[54:57], v[168:171], v[184:187], v[54:57]
	v_mfma_f32_16x16x32_bf16 v[50:53], v[176:179], v[184:187], v[50:53]
	v_mfma_f32_16x16x32_bf16 v[38:41], v[168:171], v[192:195], v[38:41]
	v_mfma_f32_16x16x32_bf16 v[34:37], v[176:179], v[192:195], v[34:37]
	v_mfma_f32_16x16x32_bf16 v[22:25], v[168:171], v[200:203], v[22:25]
	v_mfma_f32_16x16x32_bf16 v[18:21], v[176:179], v[200:203], v[18:21]
	v_mfma_f32_16x16x32_bf16 v[6:9], v[168:171], v[208:211], v[6:9]
	v_mfma_f32_16x16x32_bf16 v[2:5], v[176:179], v[208:211], v[2:5]
	v_mfma_f32_16x16x32_bf16 v[54:57], v[172:175], v[188:191], v[54:57]
	v_mfma_f32_16x16x32_bf16 v[50:53], v[180:183], v[188:191], v[50:53]
	v_mfma_f32_16x16x32_bf16 v[38:41], v[172:175], v[196:199], v[38:41]
	v_mfma_f32_16x16x32_bf16 v[34:37], v[180:183], v[196:199], v[34:37]
	v_mfma_f32_16x16x32_bf16 v[22:25], v[172:175], v[204:207], v[22:25]
	v_mfma_f32_16x16x32_bf16 v[18:21], v[180:183], v[204:207], v[18:21]
	v_mfma_f32_16x16x32_bf16 v[6:9], v[172:175], v[212:215], v[6:9]
	v_mfma_f32_16x16x32_bf16 v[2:5], v[180:183], v[212:215], v[2:5]
	s_setprio 0
	s_barrier
	s_add_i32 s50, s50, 2
	s_add_u32 s24, s24, 0x100
	s_addc_u32 s25, s25, 0
	s_add_u32 s48, s48, 0x100
	s_addc_u32 s49, s49, 0
	s_cmp_lt_u32 s50, 62
	s_cbranch_scc1 .LBB0_1007
	s_nop 0
	s_nop 0
	s_nop 0
	s_nop 0
	s_nop 0
	s_nop 0
	s_nop 0
	s_nop 0
	s_nop 0
	s_nop 0
	s_nop 0
	s_nop 0
	s_nop 0
	s_nop 0
	s_nop 0
	s_nop 0
	s_andn2_b64 vcc, exec, s[12:13]
	s_cbranch_vccnz .LBB0_1010
	s_barrier

.LBB0_1103:
	ds_read_b128 v[152:155], v148
	ds_read_b128 v[156:159], v148 offset:1024
	ds_read_b128 v[160:163], v148 offset:2048
	ds_read_b128 v[164:167], v148 offset:3072
	ds_read_b128 v[168:171], v149
	ds_read_b128 v[172:175], v149 offset:1024
	ds_read_b128 v[176:179], v149 offset:2048
	ds_read_b128 v[180:183], v149 offset:3072
	s_add_u32 s24, s22, 0xfff00080
	s_addc_u32 s25, s23, -1
	s_cmp_eq_u32 s48, 60
	s_cselect_b32 s27, s15, s25
	s_cselect_b32 s26, s44, s24
	s_cselect_b32 s25, s13, s47
	s_cselect_b32 s24, s45, s46
	v_lshl_add_u64 v[216:217], s[22:23], 0, v[138:139]
	s_add_i32 m0, s31, 0xc000
	ds_read_b128 v[184:187], v150
	ds_read_b128 v[188:191], v150 offset:1024
	ds_read_b128 v[192:195], v150 offset:2048
	ds_read_b128 v[196:199], v150 offset:3072
	ds_read_b128 v[200:203], v150 offset:4096
	ds_read_b128 v[204:207], v150 offset:5120
	ds_read_b128 v[208:211], v150 offset:6144
	ds_read_b128 v[212:215], v150 offset:7168
	global_load_lds_dwordx4 v[216:217], off
	s_add_i32 m0, s31, 0xe000
	v_lshl_add_u64 v[216:217], s[22:23], 0, v[140:141]
	global_load_lds_dwordx4 v[216:217], off
	s_waitcnt vmcnt(8)
	s_waitcnt lgkmcnt(0)
	s_barrier
	s_setprio 1
	s_waitcnt lgkmcnt(0)
	v_mfma_f32_16x16x32_bf16 v[126:129], v[152:155], v[184:187], v[126:129]
	v_mfma_f32_16x16x32_bf16 v[122:125], v[160:163], v[184:187], v[122:125]
	v_mfma_f32_16x16x32_bf16 v[110:113], v[152:155], v[192:195], v[110:113]
	v_mfma_f32_16x16x32_bf16 v[106:109], v[160:163], v[192:195], v[106:109]
	v_mfma_f32_16x16x32_bf16 v[94:97], v[152:155], v[200:203], v[94:97]
	v_mfma_f32_16x16x32_bf16 v[90:93], v[160:163], v[200:203], v[90:93]
	v_mfma_f32_16x16x32_bf16 v[78:81], v[152:155], v[208:211], v[78:81]
	v_mfma_f32_16x16x32_bf16 v[74:77], v[160:163], v[208:211], v[74:77]
	v_mfma_f32_16x16x32_bf16 v[126:129], v[156:159], v[188:191], v[126:129]
	v_mfma_f32_16x16x32_bf16 v[122:125], v[164:167], v[188:191], v[122:125]
	v_mfma_f32_16x16x32_bf16 v[110:113], v[156:159], v[196:199], v[110:113]
	v_mfma_f32_16x16x32_bf16 v[106:109], v[164:167], v[196:199], v[106:109]
	v_mfma_f32_16x16x32_bf16 v[94:97], v[156:159], v[204:207], v[94:97]
	v_mfma_f32_16x16x32_bf16 v[90:93], v[164:167], v[204:207], v[90:93]
	v_mfma_f32_16x16x32_bf16 v[78:81], v[156:159], v[212:215], v[78:81]
	v_mfma_f32_16x16x32_bf16 v[74:77], v[164:167], v[212:215], v[74:77]
	v_mfma_f32_16x16x32_bf16 v[118:121], v[168:171], v[184:187], v[118:121]
	v_mfma_f32_16x16x32_bf16 v[114:117], v[176:179], v[184:187], v[114:117]
	v_mfma_f32_16x16x32_bf16 v[102:105], v[168:171], v[192:195], v[102:105]
	v_mfma_f32_16x16x32_bf16 v[98:101], v[176:179], v[192:195], v[98:101]
	v_mfma_f32_16x16x32_bf16 v[86:89], v[168:171], v[200:203], v[86:89]
	v_mfma_f32_16x16x32_bf16 v[82:85], v[176:179], v[200:203], v[82:85]
	v_mfma_f32_16x16x32_bf16 v[70:73], v[168:171], v[208:211], v[70:73]
	v_mfma_f32_16x16x32_bf16 v[66:69], v[176:179], v[208:211], v[66:69]
	v_mfma_f32_16x16x32_bf16 v[118:121], v[172:175], v[188:191], v[118:121]
	v_mfma_f32_16x16x32_bf16 v[114:117], v[180:183], v[188:191], v[114:117]
	v_mfma_f32_16x16x32_bf16 v[102:105], v[172:175], v[196:199], v[102:105]
	v_mfma_f32_16x16x32_bf16 v[98:101], v[180:183], v[196:199], v[98:101]
	v_mfma_f32_16x16x32_bf16 v[86:89], v[172:175], v[204:207], v[86:89]
	v_mfma_f32_16x16x32_bf16 v[82:85], v[180:183], v[204:207], v[82:85]
	v_mfma_f32_16x16x32_bf16 v[70:73], v[172:175], v[212:215], v[70:73]
	v_mfma_f32_16x16x32_bf16 v[66:69], v[180:183], v[212:215], v[66:69]
	s_setprio 0
	s_barrier
	s_add_i32 s49, s42, s30
	v_lshl_add_u64 v[216:217], s[24:25], 0, v[134:135]
	s_mov_b32 m0, s49
	ds_read_b128 v[184:187], v150 offset:16384
	ds_read_b128 v[188:191], v150 offset:17408
	ds_read_b128 v[192:195], v150 offset:18432
	ds_read_b128 v[196:199], v150 offset:19456
	ds_read_b128 v[200:203], v150 offset:20480
	ds_read_b128 v[204:207], v150 offset:21504
	ds_read_b128 v[208:211], v150 offset:22528
	ds_read_b128 v[212:215], v150 offset:23552
	global_load_lds_dwordx4 v[216:217], off
	s_add_i32 m0, s49, 0x2000
	s_add_u32 s50, s24, 0x100000
	v_lshl_add_u64 v[218:219], s[24:25], 0, v[130:131]
	s_addc_u32 s51, s25, 0
	s_add_i32 s49, s43, s30
	global_load_lds_dwordx4 v[218:219], off
	v_lshl_add_u64 v[220:221], s[50:51], 0, v[134:135]
	s_mov_b32 m0, s49
	v_lshl_add_u64 v[222:223], s[26:27], 0, v[132:133]
	global_load_lds_dwordx4 v[220:221], off
	s_add_i32 m0, s49, 0x2000
	v_lshl_add_u64 v[220:221], s[50:51], 0, v[130:131]
	global_load_lds_dwordx4 v[220:221], off
	s_mov_b32 m0, s31
	v_lshl_add_u64 v[220:221], s[26:27], 0, v[136:137]
	global_load_lds_dwordx4 v[220:221], off
	s_mov_b32 m0, s33
	s_nop 0
	global_load_lds_dwordx4 v[222:223], off
	s_waitcnt vmcnt(8)
	s_waitcnt lgkmcnt(0)
	s_barrier
	s_setprio 1
	s_waitcnt lgkmcnt(0)
	v_mfma_f32_16x16x32_bf16 v[62:65], v[152:155], v[184:187], v[62:65]
	v_mfma_f32_16x16x32_bf16 v[58:61], v[160:163], v[184:187], v[58:61]
	v_mfma_f32_16x16x32_bf16 v[46:49], v[152:155], v[192:195], v[46:49]
	v_mfma_f32_16x16x32_bf16 v[42:45], v[160:163], v[192:195], v[42:45]
	v_mfma_f32_16x16x32_bf16 v[30:33], v[152:155], v[200:203], v[30:33]
	v_mfma_f32_16x16x32_bf16 v[26:29], v[160:163], v[200:203], v[26:29]
	v_mfma_f32_16x16x32_bf16 v[22:25], v[152:155], v[208:211], v[22:25]
	v_mfma_f32_16x16x32_bf16 v[18:21], v[160:163], v[208:211], v[18:21]
	v_mfma_f32_16x16x32_bf16 v[62:65], v[156:159], v[188:191], v[62:65]
	v_mfma_f32_16x16x32_bf16 v[58:61], v[164:167], v[188:191], v[58:61]
	v_mfma_f32_16x16x32_bf16 v[46:49], v[156:159], v[196:199], v[46:49]
	v_mfma_f32_16x16x32_bf16 v[42:45], v[164:167], v[196:199], v[42:45]
	v_mfma_f32_16x16x32_bf16 v[30:33], v[156:159], v[204:207], v[30:33]
	v_mfma_f32_16x16x32_bf16 v[26:29], v[164:167], v[204:207], v[26:29]
	v_mfma_f32_16x16x32_bf16 v[22:25], v[156:159], v[212:215], v[22:25]
	v_mfma_f32_16x16x32_bf16 v[18:21], v[164:167], v[212:215], v[18:21]
	v_mfma_f32_16x16x32_bf16 v[54:57], v[168:171], v[184:187], v[54:57]
	v_mfma_f32_16x16x32_bf16 v[50:53], v[176:179], v[184:187], v[50:53]
	v_mfma_f32_16x16x32_bf16 v[38:41], v[168:171], v[192:195], v[38:41]
	v_mfma_f32_16x16x32_bf16 v[34:37], v[176:179], v[192:195], v[34:37]
	v_mfma_f32_16x16x32_bf16 v[14:17], v[168:171], v[200:203], v[14:17]
	v_mfma_f32_16x16x32_bf16 v[10:13], v[176:179], v[200:203], v[10:13]
	v_mfma_f32_16x16x32_bf16 v[6:9], v[168:171], v[208:211], v[6:9]
	v_mfma_f32_16x16x32_bf16 v[2:5], v[176:179], v[208:211], v[2:5]
	v_mfma_f32_16x16x32_bf16 v[54:57], v[172:175], v[188:191], v[54:57]
	v_mfma_f32_16x16x32_bf16 v[50:53], v[180:183], v[188:191], v[50:53]
	v_mfma_f32_16x16x32_bf16 v[38:41], v[172:175], v[196:199], v[38:41]
	v_mfma_f32_16x16x32_bf16 v[34:37], v[180:183], v[196:199], v[34:37]
	v_mfma_f32_16x16x32_bf16 v[14:17], v[172:175], v[204:207], v[14:17]
	v_mfma_f32_16x16x32_bf16 v[10:13], v[180:183], v[204:207], v[10:13]
	v_mfma_f32_16x16x32_bf16 v[6:9], v[172:175], v[212:215], v[6:9]
	v_mfma_f32_16x16x32_bf16 v[2:5], v[180:183], v[212:215], v[2:5]
	s_setprio 0
	s_barrier
	s_add_i32 s49, 0, 0x18000
	s_add_i32 s50, 0, 0x1c000
	v_add_u32_e32 v164, s49, v147
	v_add_u32_e32 v180, s50, v147
	ds_read_b128 v[152:155], v164
	ds_read_b128 v[156:159], v164 offset:1024
	ds_read_b128 v[160:163], v164 offset:2048
	ds_read_b128 v[164:167], v164 offset:3072
	ds_read_b128 v[168:171], v180
	ds_read_b128 v[172:175], v180 offset:1024
	ds_read_b128 v[176:179], v180 offset:2048
	ds_read_b128 v[180:183], v180 offset:3072
	s_add_u32 s26, s26, 0x100000
	s_addc_u32 s27, s27, 0
	s_mov_b32 m0, s34
	v_lshl_add_u64 v[224:225], s[26:27], 0, v[136:137]
	ds_read_b128 v[184:187], v150 offset:32768
	ds_read_b128 v[188:191], v150 offset:33792
	ds_read_b128 v[192:195], v150 offset:34816
	ds_read_b128 v[196:199], v150 offset:35840
	ds_read_b128 v[200:203], v150 offset:36864
	ds_read_b128 v[204:207], v150 offset:37888
	ds_read_b128 v[208:211], v150 offset:38912
	ds_read_b128 v[212:215], v150 offset:39936
	global_load_lds_dwordx4 v[224:225], off
	s_mov_b32 m0, s35
	v_lshl_add_u64 v[224:225], s[26:27], 0, v[132:133]
	global_load_lds_dwordx4 v[224:225], off
	s_waitcnt vmcnt(8)
	s_waitcnt lgkmcnt(0)
	s_barrier
	s_setprio 1
	s_waitcnt lgkmcnt(0)
	v_mfma_f32_16x16x32_bf16 v[126:129], v[152:155], v[184:187], v[126:129]
	v_mfma_f32_16x16x32_bf16 v[122:125], v[160:163], v[184:187], v[122:125]
	v_mfma_f32_16x16x32_bf16 v[110:113], v[152:155], v[192:195], v[110:113]
	v_mfma_f32_16x16x32_bf16 v[106:109], v[160:163], v[192:195], v[106:109]
	v_mfma_f32_16x16x32_bf16 v[94:97], v[152:155], v[200:203], v[94:97]
	v_mfma_f32_16x16x32_bf16 v[90:93], v[160:163], v[200:203], v[90:93]
	v_mfma_f32_16x16x32_bf16 v[78:81], v[152:155], v[208:211], v[78:81]
	v_mfma_f32_16x16x32_bf16 v[74:77], v[160:163], v[208:211], v[74:77]
	v_mfma_f32_16x16x32_bf16 v[126:129], v[156:159], v[188:191], v[126:129]
	v_mfma_f32_16x16x32_bf16 v[122:125], v[164:167], v[188:191], v[122:125]
	v_mfma_f32_16x16x32_bf16 v[110:113], v[156:159], v[196:199], v[110:113]
	v_mfma_f32_16x16x32_bf16 v[106:109], v[164:167], v[196:199], v[106:109]
	v_mfma_f32_16x16x32_bf16 v[94:97], v[156:159], v[204:207], v[94:97]
	v_mfma_f32_16x16x32_bf16 v[90:93], v[164:167], v[204:207], v[90:93]
	v_mfma_f32_16x16x32_bf16 v[78:81], v[156:159], v[212:215], v[78:81]
	v_mfma_f32_16x16x32_bf16 v[74:77], v[164:167], v[212:215], v[74:77]
	v_mfma_f32_16x16x32_bf16 v[118:121], v[168:171], v[184:187], v[118:121]
	v_mfma_f32_16x16x32_bf16 v[114:117], v[176:179], v[184:187], v[114:117]
	v_mfma_f32_16x16x32_bf16 v[102:105], v[168:171], v[192:195], v[102:105]
	v_mfma_f32_16x16x32_bf16 v[98:101], v[176:179], v[192:195], v[98:101]
	v_mfma_f32_16x16x32_bf16 v[86:89], v[168:171], v[200:203], v[86:89]
	v_mfma_f32_16x16x32_bf16 v[82:85], v[176:179], v[200:203], v[82:85]
	v_mfma_f32_16x16x32_bf16 v[70:73], v[168:171], v[208:211], v[70:73]
	v_mfma_f32_16x16x32_bf16 v[66:69], v[176:179], v[208:211], v[66:69]
	v_mfma_f32_16x16x32_bf16 v[118:121], v[172:175], v[188:191], v[118:121]
	v_mfma_f32_16x16x32_bf16 v[114:117], v[180:183], v[188:191], v[114:117]
	v_mfma_f32_16x16x32_bf16 v[102:105], v[172:175], v[196:199], v[102:105]
	v_mfma_f32_16x16x32_bf16 v[98:101], v[180:183], v[196:199], v[98:101]
	v_mfma_f32_16x16x32_bf16 v[86:89], v[172:175], v[204:207], v[86:89]
	v_mfma_f32_16x16x32_bf16 v[82:85], v[180:183], v[204:207], v[82:85]
	v_mfma_f32_16x16x32_bf16 v[70:73], v[172:175], v[212:215], v[70:73]
	v_mfma_f32_16x16x32_bf16 v[66:69], v[180:183], v[212:215], v[66:69]
	s_setprio 0
	s_barrier
	s_add_i32 s26, s49, s30
	v_lshl_add_u64 v[216:217], v[216:217], 0, s[8:9]
	s_mov_b32 m0, s26
	ds_read_b128 v[184:187], v150 offset:49152
	ds_read_b128 v[188:191], v150 offset:50176
	ds_read_b128 v[192:195], v150 offset:51200
	ds_read_b128 v[196:199], v150 offset:52224
	ds_read_b128 v[200:203], v150 offset:53248
	ds_read_b128 v[204:207], v150 offset:54272
	ds_read_b128 v[208:211], v150 offset:55296
	ds_read_b128 v[212:215], v150 offset:56320
	global_load_lds_dwordx4 v[216:217], off
	s_add_i32 m0, s26, 0x2000
	s_add_u32 s24, s24, 0x100080
	v_lshl_add_u64 v[216:217], v[218:219], 0, s[8:9]
	s_addc_u32 s25, s25, 0
	s_add_i32 s26, s50, s30
	global_load_lds_dwordx4 v[216:217], off
	s_mov_b32 m0, s26
	v_lshl_add_u64 v[216:217], s[24:25], 0, v[134:135]
	global_load_lds_dwordx4 v[216:217], off
	s_add_i32 m0, s26, 0x2000
	v_lshl_add_u64 v[216:217], s[24:25], 0, v[130:131]
	global_load_lds_dwordx4 v[216:217], off
	s_mov_b32 m0, s37
	v_lshl_add_u64 v[216:217], v[220:221], 0, s[8:9]
	global_load_lds_dwordx4 v[216:217], off
	s_mov_b32 m0, s40
	v_lshl_add_u64 v[216:217], v[222:223], 0, s[8:9]
	global_load_lds_dwordx4 v[216:217], off
	s_waitcnt vmcnt(8)
	s_waitcnt lgkmcnt(0)
	s_barrier
	s_setprio 1
	s_waitcnt lgkmcnt(0)
	v_mfma_f32_16x16x32_bf16 v[62:65], v[152:155], v[184:187], v[62:65]
	v_mfma_f32_16x16x32_bf16 v[58:61], v[160:163], v[184:187], v[58:61]
	v_mfma_f32_16x16x32_bf16 v[46:49], v[152:155], v[192:195], v[46:49]
	v_mfma_f32_16x16x32_bf16 v[42:45], v[160:163], v[192:195], v[42:45]
	v_mfma_f32_16x16x32_bf16 v[30:33], v[152:155], v[200:203], v[30:33]
	v_mfma_f32_16x16x32_bf16 v[26:29], v[160:163], v[200:203], v[26:29]
	v_mfma_f32_16x16x32_bf16 v[22:25], v[152:155], v[208:211], v[22:25]
	v_mfma_f32_16x16x32_bf16 v[18:21], v[160:163], v[208:211], v[18:21]
	v_mfma_f32_16x16x32_bf16 v[62:65], v[156:159], v[188:191], v[62:65]
	v_mfma_f32_16x16x32_bf16 v[58:61], v[164:167], v[188:191], v[58:61]
	v_mfma_f32_16x16x32_bf16 v[46:49], v[156:159], v[196:199], v[46:49]
	v_mfma_f32_16x16x32_bf16 v[42:45], v[164:167], v[196:199], v[42:45]
	v_mfma_f32_16x16x32_bf16 v[30:33], v[156:159], v[204:207], v[30:33]
	v_mfma_f32_16x16x32_bf16 v[26:29], v[164:167], v[204:207], v[26:29]
	v_mfma_f32_16x16x32_bf16 v[22:25], v[156:159], v[212:215], v[22:25]
	v_mfma_f32_16x16x32_bf16 v[18:21], v[164:167], v[212:215], v[18:21]
	v_mfma_f32_16x16x32_bf16 v[54:57], v[168:171], v[184:187], v[54:57]
	v_mfma_f32_16x16x32_bf16 v[50:53], v[176:179], v[184:187], v[50:53]
	v_mfma_f32_16x16x32_bf16 v[38:41], v[168:171], v[192:195], v[38:41]
	v_mfma_f32_16x16x32_bf16 v[34:37], v[176:179], v[192:195], v[34:37]
	v_mfma_f32_16x16x32_bf16 v[14:17], v[168:171], v[200:203], v[14:17]
	v_mfma_f32_16x16x32_bf16 v[10:13], v[176:179], v[200:203], v[10:13]
	v_mfma_f32_16x16x32_bf16 v[6:9], v[168:171], v[208:211], v[6:9]
	v_mfma_f32_16x16x32_bf16 v[2:5], v[176:179], v[208:211], v[2:5]
	v_mfma_f32_16x16x32_bf16 v[54:57], v[172:175], v[188:191], v[54:57]
	v_mfma_f32_16x16x32_bf16 v[50:53], v[180:183], v[188:191], v[50:53]
	v_mfma_f32_16x16x32_bf16 v[38:41], v[172:175], v[196:199], v[38:41]
	v_mfma_f32_16x16x32_bf16 v[34:37], v[180:183], v[196:199], v[34:37]
	v_mfma_f32_16x16x32_bf16 v[14:17], v[172:175], v[204:207], v[14:17]
	v_mfma_f32_16x16x32_bf16 v[10:13], v[180:183], v[204:207], v[10:13]
	v_mfma_f32_16x16x32_bf16 v[6:9], v[172:175], v[212:215], v[6:9]
	v_mfma_f32_16x16x32_bf16 v[2:5], v[180:183], v[212:215], v[2:5]
	s_setprio 0
	s_barrier
	s_add_i32 s48, s48, 2
	s_add_u32 s22, s22, 0x100
	s_addc_u32 s23, s23, 0
	s_add_u32 s46, s46, 0x100
	s_addc_u32 s47, s47, 0
	s_cmp_lt_u32 s48, 62
	s_cbranch_scc1 .LBB0_1103
	s_nop 0
	s_nop 0
	s_nop 0
	s_nop 0
	s_nop 0
	s_nop 0
	s_nop 0
	s_nop 0
	s_nop 0
	s_nop 0
	s_nop 0
	s_nop 0
	s_nop 0
	s_nop 0
	s_nop 0
	s_nop 0
	s_andn2_b64 vcc, exec, s[10:11]
	s_cbranch_vccnz .LBB0_1106
	s_barrier

.LBB0_1262:
	ds_read_b128 v[50:53], v181
	ds_read_b128 v[54:57], v181 offset:1024
	ds_read_b128 v[138:141], v181 offset:2048
	ds_read_b128 v[142:145], v181 offset:3072
	ds_read_b128 v[168:171], v185
	ds_read_b128 v[174:177], v185 offset:1024
	ds_read_b128 v[190:193], v185 offset:2048
	ds_read_b128 v[194:197], v185 offset:3072
	s_add_u32 s28, s26, 0xfff80080
	s_addc_u32 s29, s27, -1
	s_cmp_eq_u32 s54, 28
	s_cselect_b32 s31, s19, s29
	s_cselect_b32 s30, s50, s28
	s_cselect_b32 s29, s17, s53
	s_cselect_b32 s28, s51, s52
	v_lshl_add_u64 v[178:179], s[26:27], 0, v[158:159]
	s_add_i32 m0, s37, 0xc000
	ds_read_b128 v[198:201], v189
	ds_read_b128 v[202:205], v189 offset:1024
	ds_read_b128 v[206:209], v189 offset:2048
	ds_read_b128 v[210:213], v189 offset:3072
	ds_read_b128 v[214:217], v189 offset:4096
	ds_read_b128 v[218:221], v189 offset:5120
	ds_read_b128 v[222:225], v189 offset:6144
	ds_read_b128 v[226:229], v189 offset:7168
	global_load_lds_dwordx4 v[178:179], off
	s_add_i32 m0, s37, 0xe000
	v_lshl_add_u64 v[178:179], s[26:27], 0, v[160:161]
	global_load_lds_dwordx4 v[178:179], off
	s_waitcnt vmcnt(8)
	s_waitcnt lgkmcnt(0)
	s_barrier
	s_setprio 1
	s_waitcnt lgkmcnt(0)
	v_mfma_i32_16x16x64_i8 v[134:137], v[50:53], v[198:201], v[134:137]
	v_mfma_i32_16x16x64_i8 v[130:133], v[138:141], v[198:201], v[130:133]
	v_mfma_i32_16x16x64_i8 v[118:121], v[50:53], v[206:209], v[118:121]
	v_mfma_i32_16x16x64_i8 v[114:117], v[138:141], v[206:209], v[114:117]
	v_mfma_i32_16x16x64_i8 v[102:105], v[50:53], v[214:217], v[102:105]
	v_mfma_i32_16x16x64_i8 v[98:101], v[138:141], v[214:217], v[98:101]
	v_mfma_i32_16x16x64_i8 v[86:89], v[50:53], v[222:225], v[86:89]
	v_mfma_i32_16x16x64_i8 v[82:85], v[138:141], v[222:225], v[82:85]
	v_mfma_i32_16x16x64_i8 v[134:137], v[54:57], v[202:205], v[134:137]
	v_mfma_i32_16x16x64_i8 v[130:133], v[142:145], v[202:205], v[130:133]
	v_mfma_i32_16x16x64_i8 v[118:121], v[54:57], v[210:213], v[118:121]
	v_mfma_i32_16x16x64_i8 v[114:117], v[142:145], v[210:213], v[114:117]
	v_mfma_i32_16x16x64_i8 v[102:105], v[54:57], v[218:221], v[102:105]
	v_mfma_i32_16x16x64_i8 v[98:101], v[142:145], v[218:221], v[98:101]
	v_mfma_i32_16x16x64_i8 v[86:89], v[54:57], v[226:229], v[86:89]
	v_mfma_i32_16x16x64_i8 v[82:85], v[142:145], v[226:229], v[82:85]
	v_mfma_i32_16x16x64_i8 v[126:129], v[168:171], v[198:201], v[126:129]
	v_mfma_i32_16x16x64_i8 v[122:125], v[190:193], v[198:201], v[122:125]
	v_mfma_i32_16x16x64_i8 v[110:113], v[168:171], v[206:209], v[110:113]
	v_mfma_i32_16x16x64_i8 v[106:109], v[190:193], v[206:209], v[106:109]
	v_mfma_i32_16x16x64_i8 v[94:97], v[168:171], v[214:217], v[94:97]
	v_mfma_i32_16x16x64_i8 v[90:93], v[190:193], v[214:217], v[90:93]
	v_mfma_i32_16x16x64_i8 v[78:81], v[168:171], v[222:225], v[78:81]
	v_mfma_i32_16x16x64_i8 v[74:77], v[190:193], v[222:225], v[74:77]
	v_mfma_i32_16x16x64_i8 v[126:129], v[174:177], v[202:205], v[126:129]
	v_mfma_i32_16x16x64_i8 v[122:125], v[194:197], v[202:205], v[122:125]
	v_mfma_i32_16x16x64_i8 v[110:113], v[174:177], v[210:213], v[110:113]
	v_mfma_i32_16x16x64_i8 v[106:109], v[194:197], v[210:213], v[106:109]
	v_mfma_i32_16x16x64_i8 v[94:97], v[174:177], v[218:221], v[94:97]
	v_mfma_i32_16x16x64_i8 v[90:93], v[194:197], v[218:221], v[90:93]
	v_mfma_i32_16x16x64_i8 v[78:81], v[174:177], v[226:229], v[78:81]
	v_mfma_i32_16x16x64_i8 v[74:77], v[194:197], v[226:229], v[74:77]
	s_setprio 0
	s_barrier
	s_add_i32 s55, s47, s35
	v_lshl_add_u64 v[178:179], s[28:29], 0, v[150:151]
	s_mov_b32 m0, s55
	ds_read_b128 v[198:201], v189 offset:16384
	ds_read_b128 v[202:205], v189 offset:17408
	ds_read_b128 v[206:209], v189 offset:18432
	ds_read_b128 v[210:213], v189 offset:19456
	ds_read_b128 v[214:217], v189 offset:20480
	ds_read_b128 v[218:221], v189 offset:21504
	ds_read_b128 v[222:225], v189 offset:22528
	ds_read_b128 v[226:229], v189 offset:23552
	global_load_lds_dwordx4 v[178:179], off
	s_add_i32 m0, s55, 0x2000
	s_add_u32 s56, s28, 0x80000
	v_lshl_add_u64 v[182:183], s[28:29], 0, v[146:147]
	s_addc_u32 s57, s29, 0
	s_add_i32 s55, s48, s35
	global_load_lds_dwordx4 v[182:183], off
	v_lshl_add_u64 v[186:187], s[56:57], 0, v[150:151]
	s_mov_b32 m0, s55
	v_lshl_add_u64 v[230:231], s[30:31], 0, v[148:149]
	global_load_lds_dwordx4 v[186:187], off
	s_add_i32 m0, s55, 0x2000
	v_lshl_add_u64 v[186:187], s[56:57], 0, v[146:147]
	global_load_lds_dwordx4 v[186:187], off
	s_mov_b32 m0, s37
	v_lshl_add_u64 v[186:187], s[30:31], 0, v[152:153]
	global_load_lds_dwordx4 v[186:187], off
	s_mov_b32 m0, s40
	s_nop 0
	global_load_lds_dwordx4 v[230:231], off
	s_waitcnt vmcnt(8)
	s_waitcnt lgkmcnt(0)
	s_barrier
	s_setprio 1
	s_waitcnt lgkmcnt(0)
	v_mfma_i32_16x16x64_i8 v[70:73], v[50:53], v[198:201], v[70:73]
	v_mfma_i32_16x16x64_i8 v[66:69], v[138:141], v[198:201], v[66:69]
	v_mfma_i32_16x16x64_i8 v[46:49], v[50:53], v[206:209], v[46:49]
	v_mfma_i32_16x16x64_i8 v[42:45], v[138:141], v[206:209], v[42:45]
	v_mfma_i32_16x16x64_i8 v[30:33], v[50:53], v[214:217], v[30:33]
	v_mfma_i32_16x16x64_i8 v[26:29], v[138:141], v[214:217], v[26:29]
	v_mfma_i32_16x16x64_i8 v[14:17], v[50:53], v[222:225], v[14:17]
	v_mfma_i32_16x16x64_i8 v[10:13], v[138:141], v[222:225], v[10:13]
	v_mfma_i32_16x16x64_i8 v[70:73], v[54:57], v[202:205], v[70:73]
	v_mfma_i32_16x16x64_i8 v[66:69], v[142:145], v[202:205], v[66:69]
	v_mfma_i32_16x16x64_i8 v[46:49], v[54:57], v[210:213], v[46:49]
	v_mfma_i32_16x16x64_i8 v[42:45], v[142:145], v[210:213], v[42:45]
	v_mfma_i32_16x16x64_i8 v[30:33], v[54:57], v[218:221], v[30:33]
	v_mfma_i32_16x16x64_i8 v[26:29], v[142:145], v[218:221], v[26:29]
	v_mfma_i32_16x16x64_i8 v[14:17], v[54:57], v[226:229], v[14:17]
	v_mfma_i32_16x16x64_i8 v[10:13], v[142:145], v[226:229], v[10:13]
	v_mfma_i32_16x16x64_i8 v[38:41], v[168:171], v[206:209], v[38:41]
	v_mfma_i32_16x16x64_i8 v[34:37], v[190:193], v[206:209], v[34:37]
	v_mfma_i32_16x16x64_i8 v[22:25], v[168:171], v[214:217], v[22:25]
	v_mfma_i32_16x16x64_i8 v[18:21], v[190:193], v[214:217], v[18:21]
	v_mfma_i32_16x16x64_i8 v[6:9], v[168:171], v[222:225], v[6:9]
	v_mfma_i32_16x16x64_i8 v[2:5], v[190:193], v[222:225], v[2:5]
	v_mfma_i32_16x16x64_i8 v[50:53], v[168:171], v[198:201], v[62:65]
	v_mfma_i32_16x16x64_i8 v[54:57], v[190:193], v[198:201], v[58:61]
	v_mfma_i32_16x16x64_i8 v[38:41], v[174:177], v[210:213], v[38:41]
	v_mfma_i32_16x16x64_i8 v[34:37], v[194:197], v[210:213], v[34:37]
	v_mfma_i32_16x16x64_i8 v[22:25], v[174:177], v[218:221], v[22:25]
	v_mfma_i32_16x16x64_i8 v[18:21], v[194:197], v[218:221], v[18:21]
	v_mfma_i32_16x16x64_i8 v[6:9], v[174:177], v[226:229], v[6:9]
	v_mfma_i32_16x16x64_i8 v[2:5], v[194:197], v[226:229], v[2:5]
	v_mfma_i32_16x16x64_i8 v[50:53], v[174:177], v[202:205], v[50:53]
	v_mfma_i32_16x16x64_i8 v[54:57], v[194:197], v[202:205], v[54:57]
	s_setprio 0
	s_barrier
	s_add_i32 s55, 0, 0x18000
	s_add_i32 s56, 0, 0x1c000
	v_add_u32_e32 v142, s55, v167
	v_add_u32_e32 v154, s56, v167
	ds_read_b128 v[58:61], v142
	ds_read_b128 v[62:65], v142 offset:1024
	ds_read_b128 v[138:141], v142 offset:2048
	ds_read_b128 v[142:145], v142 offset:3072
	ds_read_b128 v[168:171], v154
	ds_read_b128 v[174:177], v154 offset:1024
	ds_read_b128 v[190:193], v154 offset:2048
	ds_read_b128 v[194:197], v154 offset:3072
	s_add_u32 s30, s30, 0x80000
	s_addc_u32 s31, s31, 0
	s_mov_b32 m0, s41
	v_lshl_add_u64 v[232:233], s[30:31], 0, v[152:153]
	ds_read_b128 v[198:201], v189 offset:32768
	ds_read_b128 v[202:205], v189 offset:33792
	ds_read_b128 v[206:209], v189 offset:34816
	ds_read_b128 v[210:213], v189 offset:35840
	ds_read_b128 v[214:217], v189 offset:36864
	ds_read_b128 v[218:221], v189 offset:37888
	ds_read_b128 v[222:225], v189 offset:38912
	ds_read_b128 v[226:229], v189 offset:39936
	global_load_lds_dwordx4 v[232:233], off
	s_mov_b32 m0, s42
	v_lshl_add_u64 v[232:233], s[30:31], 0, v[148:149]
	global_load_lds_dwordx4 v[232:233], off
	s_waitcnt vmcnt(8)
	s_waitcnt lgkmcnt(0)
	s_barrier
	s_setprio 1
	s_waitcnt lgkmcnt(0)
	v_mfma_i32_16x16x64_i8 v[134:137], v[58:61], v[198:201], v[134:137]
	v_mfma_i32_16x16x64_i8 v[130:133], v[138:141], v[198:201], v[130:133]
	v_mfma_i32_16x16x64_i8 v[118:121], v[58:61], v[206:209], v[118:121]
	v_mfma_i32_16x16x64_i8 v[114:117], v[138:141], v[206:209], v[114:117]
	v_mfma_i32_16x16x64_i8 v[102:105], v[58:61], v[214:217], v[102:105]
	v_mfma_i32_16x16x64_i8 v[98:101], v[138:141], v[214:217], v[98:101]
	v_mfma_i32_16x16x64_i8 v[86:89], v[58:61], v[222:225], v[86:89]
	v_mfma_i32_16x16x64_i8 v[82:85], v[138:141], v[222:225], v[82:85]
	v_mfma_i32_16x16x64_i8 v[134:137], v[62:65], v[202:205], v[134:137]
	v_mfma_i32_16x16x64_i8 v[130:133], v[142:145], v[202:205], v[130:133]
	v_mfma_i32_16x16x64_i8 v[118:121], v[62:65], v[210:213], v[118:121]
	v_mfma_i32_16x16x64_i8 v[114:117], v[142:145], v[210:213], v[114:117]
	v_mfma_i32_16x16x64_i8 v[102:105], v[62:65], v[218:221], v[102:105]
	v_mfma_i32_16x16x64_i8 v[98:101], v[142:145], v[218:221], v[98:101]
	v_mfma_i32_16x16x64_i8 v[86:89], v[62:65], v[226:229], v[86:89]
	v_mfma_i32_16x16x64_i8 v[82:85], v[142:145], v[226:229], v[82:85]
	v_mfma_i32_16x16x64_i8 v[126:129], v[168:171], v[198:201], v[126:129]
	v_mfma_i32_16x16x64_i8 v[122:125], v[190:193], v[198:201], v[122:125]
	v_mfma_i32_16x16x64_i8 v[110:113], v[168:171], v[206:209], v[110:113]
	v_mfma_i32_16x16x64_i8 v[106:109], v[190:193], v[206:209], v[106:109]
	v_mfma_i32_16x16x64_i8 v[94:97], v[168:171], v[214:217], v[94:97]
	v_mfma_i32_16x16x64_i8 v[90:93], v[190:193], v[214:217], v[90:93]
	v_mfma_i32_16x16x64_i8 v[78:81], v[168:171], v[222:225], v[78:81]
	v_mfma_i32_16x16x64_i8 v[74:77], v[190:193], v[222:225], v[74:77]
	v_mfma_i32_16x16x64_i8 v[126:129], v[174:177], v[202:205], v[126:129]
	v_mfma_i32_16x16x64_i8 v[122:125], v[194:197], v[202:205], v[122:125]
	v_mfma_i32_16x16x64_i8 v[110:113], v[174:177], v[210:213], v[110:113]
	v_mfma_i32_16x16x64_i8 v[106:109], v[194:197], v[210:213], v[106:109]
	v_mfma_i32_16x16x64_i8 v[94:97], v[174:177], v[218:221], v[94:97]
	v_mfma_i32_16x16x64_i8 v[90:93], v[194:197], v[218:221], v[90:93]
	v_mfma_i32_16x16x64_i8 v[78:81], v[174:177], v[226:229], v[78:81]
	v_mfma_i32_16x16x64_i8 v[74:77], v[194:197], v[226:229], v[74:77]
	s_setprio 0
	s_barrier
	s_add_i32 s30, s55, s35
	v_lshl_add_u64 v[178:179], v[178:179], 0, s[12:13]
	s_mov_b32 m0, s30
	ds_read_b128 v[198:201], v189 offset:49152
	ds_read_b128 v[202:205], v189 offset:50176
	ds_read_b128 v[206:209], v189 offset:51200
	ds_read_b128 v[210:213], v189 offset:52224
	ds_read_b128 v[214:217], v189 offset:53248
	ds_read_b128 v[218:221], v189 offset:54272
	ds_read_b128 v[222:225], v189 offset:55296
	ds_read_b128 v[226:229], v189 offset:56320
	global_load_lds_dwordx4 v[178:179], off
	s_add_i32 m0, s30, 0x2000
	s_add_u32 s28, s28, 0x80080
	v_lshl_add_u64 v[178:179], v[182:183], 0, s[12:13]
	s_addc_u32 s29, s29, 0
	s_add_i32 s30, s56, s35
	global_load_lds_dwordx4 v[178:179], off
	s_mov_b32 m0, s30
	v_lshl_add_u64 v[178:179], s[28:29], 0, v[150:151]
	global_load_lds_dwordx4 v[178:179], off
	s_add_i32 m0, s30, 0x2000
	v_lshl_add_u64 v[178:179], s[28:29], 0, v[146:147]
	global_load_lds_dwordx4 v[178:179], off
	s_mov_b32 m0, s44
	v_lshl_add_u64 v[178:179], v[186:187], 0, s[12:13]
	global_load_lds_dwordx4 v[178:179], off
	s_mov_b32 m0, s45
	v_lshl_add_u64 v[178:179], v[230:231], 0, s[12:13]
	global_load_lds_dwordx4 v[178:179], off
	s_waitcnt vmcnt(8)
	s_waitcnt lgkmcnt(0)
	s_barrier
	s_setprio 1
	s_waitcnt lgkmcnt(0)
	v_mfma_i32_16x16x64_i8 v[70:73], v[58:61], v[198:201], v[70:73]
	v_mfma_i32_16x16x64_i8 v[66:69], v[138:141], v[198:201], v[66:69]
	v_mfma_i32_16x16x64_i8 v[46:49], v[58:61], v[206:209], v[46:49]
	v_mfma_i32_16x16x64_i8 v[42:45], v[138:141], v[206:209], v[42:45]
	v_mfma_i32_16x16x64_i8 v[30:33], v[58:61], v[214:217], v[30:33]
	v_mfma_i32_16x16x64_i8 v[26:29], v[138:141], v[214:217], v[26:29]
	v_mfma_i32_16x16x64_i8 v[14:17], v[58:61], v[222:225], v[14:17]
	v_mfma_i32_16x16x64_i8 v[10:13], v[138:141], v[222:225], v[10:13]
	v_mfma_i32_16x16x64_i8 v[70:73], v[62:65], v[202:205], v[70:73]
	v_mfma_i32_16x16x64_i8 v[66:69], v[142:145], v[202:205], v[66:69]
	v_mfma_i32_16x16x64_i8 v[46:49], v[62:65], v[210:213], v[46:49]
	v_mfma_i32_16x16x64_i8 v[42:45], v[142:145], v[210:213], v[42:45]
	v_mfma_i32_16x16x64_i8 v[30:33], v[62:65], v[218:221], v[30:33]
	v_mfma_i32_16x16x64_i8 v[26:29], v[142:145], v[218:221], v[26:29]
	v_mfma_i32_16x16x64_i8 v[14:17], v[62:65], v[226:229], v[14:17]
	v_mfma_i32_16x16x64_i8 v[10:13], v[142:145], v[226:229], v[10:13]
	v_mfma_i32_16x16x64_i8 v[50:53], v[168:171], v[198:201], v[50:53]
	v_mfma_i32_16x16x64_i8 v[62:65], v[174:177], v[202:205], v[50:53]
	v_mfma_i32_16x16x64_i8 v[50:53], v[190:193], v[198:201], v[54:57]
	v_mfma_i32_16x16x64_i8 v[38:41], v[168:171], v[206:209], v[38:41]
	v_mfma_i32_16x16x64_i8 v[34:37], v[190:193], v[206:209], v[34:37]
	v_mfma_i32_16x16x64_i8 v[22:25], v[168:171], v[214:217], v[22:25]
	v_mfma_i32_16x16x64_i8 v[18:21], v[190:193], v[214:217], v[18:21]
	v_mfma_i32_16x16x64_i8 v[6:9], v[168:171], v[222:225], v[6:9]
	v_mfma_i32_16x16x64_i8 v[2:5], v[190:193], v[222:225], v[2:5]
	v_mfma_i32_16x16x64_i8 v[58:61], v[194:197], v[202:205], v[50:53]
	v_mfma_i32_16x16x64_i8 v[38:41], v[174:177], v[210:213], v[38:41]
	v_mfma_i32_16x16x64_i8 v[34:37], v[194:197], v[210:213], v[34:37]
	v_mfma_i32_16x16x64_i8 v[22:25], v[174:177], v[218:221], v[22:25]
	v_mfma_i32_16x16x64_i8 v[18:21], v[194:197], v[218:221], v[18:21]
	v_mfma_i32_16x16x64_i8 v[6:9], v[174:177], v[226:229], v[6:9]
	v_mfma_i32_16x16x64_i8 v[2:5], v[194:197], v[226:229], v[2:5]
	s_setprio 0
	s_barrier
	s_add_i32 s54, s54, 2
	s_add_u32 s26, s26, 0x100
	s_addc_u32 s27, s27, 0
	s_add_u32 s52, s52, 0x100
	s_addc_u32 s53, s53, 0
	s_cmp_lt_u32 s54, 30
	s_cbranch_scc1 .LBB0_1262
	s_nop 0
	s_nop 0
	s_nop 0
	s_nop 0
	s_nop 0
	s_nop 0
	s_nop 0
	s_nop 0
	s_nop 0
	s_nop 0
	s_nop 0
	s_nop 0
	s_nop 0
	s_nop 0
	s_nop 0
	s_nop 0
	s_andn2_b64 vcc, exec, s[14:15]
	s_cbranch_vccnz .LBB0_1265
	s_barrier

.LBB0_1402:
	ds_read_b128 v[124:127], v173
	ds_read_b128 v[128:131], v173 offset:1024
	ds_read_b128 v[136:139], v173 offset:2048
	ds_read_b128 v[140:143], v173 offset:3072
	ds_read_b128 v[162:165], v174
	ds_read_b128 v[166:169], v174 offset:1024
	ds_read_b128 v[176:179], v174 offset:2048
	ds_read_b128 v[180:183], v174 offset:3072
	s_add_u32 s20, s18, 0xffea8080
	s_addc_u32 s21, s19, -1
	s_cmpk_eq_i32 s44, 0x52
	s_cselect_b32 s23, s5, s21
	s_cselect_b32 s22, s4, s20
	s_cselect_b32 s21, s17, s43
	s_cselect_b32 s20, s16, s42
	v_lshl_add_u64 v[216:217], s[18:19], 0, v[154:155]
	s_add_i32 m0, s27, 0xc000
	ds_read_b128 v[184:187], v175
	ds_read_b128 v[188:191], v175 offset:1024
	ds_read_b128 v[192:195], v175 offset:2048
	ds_read_b128 v[196:199], v175 offset:3072
	ds_read_b128 v[200:203], v175 offset:4096
	ds_read_b128 v[204:207], v175 offset:5120
	ds_read_b128 v[208:211], v175 offset:6144
	ds_read_b128 v[212:215], v175 offset:7168
	global_load_lds_dwordx4 v[216:217], off
	s_add_i32 m0, s27, 0xe000
	v_lshl_add_u64 v[216:217], s[18:19], 0, v[156:157]
	global_load_lds_dwordx4 v[216:217], off
	s_waitcnt vmcnt(8)
	s_waitcnt lgkmcnt(0)
	s_barrier
	s_setprio 1
	s_waitcnt lgkmcnt(0)
	v_mfma_i32_16x16x64_i8 v[132:135], v[124:127], v[184:187], v[132:135]
	v_mfma_i32_16x16x64_i8 v[120:123], v[136:139], v[184:187], v[120:123]
	v_mfma_i32_16x16x64_i8 v[108:111], v[124:127], v[192:195], v[108:111]
	v_mfma_i32_16x16x64_i8 v[104:107], v[136:139], v[192:195], v[104:107]
	v_mfma_i32_16x16x64_i8 v[92:95], v[124:127], v[200:203], v[92:95]
	v_mfma_i32_16x16x64_i8 v[88:91], v[136:139], v[200:203], v[88:91]
	v_mfma_i32_16x16x64_i8 v[76:79], v[124:127], v[208:211], v[76:79]
	v_mfma_i32_16x16x64_i8 v[72:75], v[136:139], v[208:211], v[72:75]
	v_mfma_i32_16x16x64_i8 v[132:135], v[128:131], v[188:191], v[132:135]
	v_mfma_i32_16x16x64_i8 v[120:123], v[140:143], v[188:191], v[120:123]
	v_mfma_i32_16x16x64_i8 v[108:111], v[128:131], v[196:199], v[108:111]
	v_mfma_i32_16x16x64_i8 v[104:107], v[140:143], v[196:199], v[104:107]
	v_mfma_i32_16x16x64_i8 v[92:95], v[128:131], v[204:207], v[92:95]
	v_mfma_i32_16x16x64_i8 v[88:91], v[140:143], v[204:207], v[88:91]
	v_mfma_i32_16x16x64_i8 v[76:79], v[128:131], v[212:215], v[76:79]
	v_mfma_i32_16x16x64_i8 v[72:75], v[140:143], v[212:215], v[72:75]
	v_mfma_i32_16x16x64_i8 v[116:119], v[162:165], v[184:187], v[116:119]
	v_mfma_i32_16x16x64_i8 v[112:115], v[176:179], v[184:187], v[112:115]
	v_mfma_i32_16x16x64_i8 v[100:103], v[162:165], v[192:195], v[100:103]
	v_mfma_i32_16x16x64_i8 v[96:99], v[176:179], v[192:195], v[96:99]
	v_mfma_i32_16x16x64_i8 v[84:87], v[162:165], v[200:203], v[84:87]
	v_mfma_i32_16x16x64_i8 v[80:83], v[176:179], v[200:203], v[80:83]
	v_mfma_i32_16x16x64_i8 v[68:71], v[162:165], v[208:211], v[68:71]
	v_mfma_i32_16x16x64_i8 v[64:67], v[176:179], v[208:211], v[64:67]
	v_mfma_i32_16x16x64_i8 v[116:119], v[166:169], v[188:191], v[116:119]
	v_mfma_i32_16x16x64_i8 v[112:115], v[180:183], v[188:191], v[112:115]
	v_mfma_i32_16x16x64_i8 v[100:103], v[166:169], v[196:199], v[100:103]
	v_mfma_i32_16x16x64_i8 v[96:99], v[180:183], v[196:199], v[96:99]
	v_mfma_i32_16x16x64_i8 v[84:87], v[166:169], v[204:207], v[84:87]
	v_mfma_i32_16x16x64_i8 v[80:83], v[180:183], v[204:207], v[80:83]
	v_mfma_i32_16x16x64_i8 v[68:71], v[166:169], v[212:215], v[68:71]
	v_mfma_i32_16x16x64_i8 v[64:67], v[180:183], v[212:215], v[64:67]
	s_setprio 0
	s_barrier
	s_add_i32 s45, s36, s24
	v_lshl_add_u64 v[216:217], s[20:21], 0, v[148:149]
	s_mov_b32 m0, s45
	ds_read_b128 v[184:187], v175 offset:16384
	ds_read_b128 v[188:191], v175 offset:17408
	ds_read_b128 v[192:195], v175 offset:18432
	ds_read_b128 v[196:199], v175 offset:19456
	ds_read_b128 v[200:203], v175 offset:20480
	ds_read_b128 v[204:207], v175 offset:21504
	ds_read_b128 v[208:211], v175 offset:22528
	ds_read_b128 v[212:215], v175 offset:23552
	global_load_lds_dwordx4 v[216:217], off
	s_add_i32 m0, s45, 0x2000
	s_add_u32 s46, s20, 0x158000
	v_lshl_add_u64 v[218:219], s[20:21], 0, v[144:145]
	s_addc_u32 s47, s21, 0
	s_add_i32 s45, s37, s24
	global_load_lds_dwordx4 v[218:219], off
	v_lshl_add_u64 v[220:221], s[46:47], 0, v[148:149]
	s_mov_b32 m0, s45
	v_lshl_add_u64 v[222:223], s[22:23], 0, v[146:147]
	global_load_lds_dwordx4 v[220:221], off
	s_add_i32 m0, s45, 0x2000
	v_lshl_add_u64 v[220:221], s[46:47], 0, v[144:145]
	global_load_lds_dwordx4 v[220:221], off
	s_mov_b32 m0, s27
	v_lshl_add_u64 v[220:221], s[22:23], 0, v[150:151]
	global_load_lds_dwordx4 v[220:221], off
	s_mov_b32 m0, s28
	s_nop 0
	global_load_lds_dwordx4 v[222:223], off
	s_waitcnt vmcnt(8)
	s_waitcnt lgkmcnt(0)
	s_barrier
	s_setprio 1
	s_waitcnt lgkmcnt(0)
	v_mfma_i32_16x16x64_i8 v[60:63], v[124:127], v[184:187], v[60:63]
	v_mfma_i32_16x16x64_i8 v[56:59], v[136:139], v[184:187], v[56:59]
	v_mfma_i32_16x16x64_i8 v[44:47], v[124:127], v[192:195], v[44:47]
	v_mfma_i32_16x16x64_i8 v[40:43], v[136:139], v[192:195], v[40:43]
	v_mfma_i32_16x16x64_i8 v[28:31], v[124:127], v[200:203], v[28:31]
	v_mfma_i32_16x16x64_i8 v[24:27], v[136:139], v[200:203], v[24:27]
	v_mfma_i32_16x16x64_i8 v[12:15], v[124:127], v[208:211], v[12:15]
	v_mfma_i32_16x16x64_i8 v[8:11], v[136:139], v[208:211], v[8:11]
	v_mfma_i32_16x16x64_i8 v[60:63], v[128:131], v[188:191], v[60:63]
	v_mfma_i32_16x16x64_i8 v[56:59], v[140:143], v[188:191], v[56:59]
	v_mfma_i32_16x16x64_i8 v[44:47], v[128:131], v[196:199], v[44:47]
	v_mfma_i32_16x16x64_i8 v[40:43], v[140:143], v[196:199], v[40:43]
	v_mfma_i32_16x16x64_i8 v[28:31], v[128:131], v[204:207], v[28:31]
	v_mfma_i32_16x16x64_i8 v[24:27], v[140:143], v[204:207], v[24:27]
	v_mfma_i32_16x16x64_i8 v[12:15], v[128:131], v[212:215], v[12:15]
	v_mfma_i32_16x16x64_i8 v[8:11], v[140:143], v[212:215], v[8:11]
	v_mfma_i32_16x16x64_i8 v[52:55], v[162:165], v[184:187], v[52:55]
	v_mfma_i32_16x16x64_i8 v[48:51], v[176:179], v[184:187], v[48:51]
	v_mfma_i32_16x16x64_i8 v[36:39], v[162:165], v[192:195], v[36:39]
	v_mfma_i32_16x16x64_i8 v[32:35], v[176:179], v[192:195], v[32:35]
	v_mfma_i32_16x16x64_i8 v[20:23], v[162:165], v[200:203], v[20:23]
	v_mfma_i32_16x16x64_i8 v[16:19], v[176:179], v[200:203], v[16:19]
	v_mfma_i32_16x16x64_i8 v[4:7], v[162:165], v[208:211], v[4:7]
	v_mfma_i32_16x16x64_i8 v[0:3], v[176:179], v[208:211], v[0:3]
	v_mfma_i32_16x16x64_i8 v[52:55], v[166:169], v[188:191], v[52:55]
	v_mfma_i32_16x16x64_i8 v[48:51], v[180:183], v[188:191], v[48:51]
	v_mfma_i32_16x16x64_i8 v[36:39], v[166:169], v[196:199], v[36:39]
	v_mfma_i32_16x16x64_i8 v[32:35], v[180:183], v[196:199], v[32:35]
	v_mfma_i32_16x16x64_i8 v[20:23], v[166:169], v[204:207], v[20:23]
	v_mfma_i32_16x16x64_i8 v[16:19], v[180:183], v[204:207], v[16:19]
	v_mfma_i32_16x16x64_i8 v[4:7], v[166:169], v[212:215], v[4:7]
	v_mfma_i32_16x16x64_i8 v[0:3], v[180:183], v[212:215], v[0:3]
	s_setprio 0
	s_barrier
	s_add_i32 s45, 0, 0x18000
	s_add_i32 s46, 0, 0x1c000
	v_add_u32_e32 v140, s45, v171
	v_add_u32_e32 v152, s46, v171
	ds_read_b128 v[124:127], v140
	ds_read_b128 v[128:131], v140 offset:1024
	ds_read_b128 v[136:139], v140 offset:2048
	ds_read_b128 v[140:143], v140 offset:3072
	ds_read_b128 v[162:165], v152
	ds_read_b128 v[166:169], v152 offset:1024
	ds_read_b128 v[176:179], v152 offset:2048
	ds_read_b128 v[180:183], v152 offset:3072
	s_add_u32 s22, s22, 0x158000
	s_addc_u32 s23, s23, 0
	s_mov_b32 m0, s29
	v_lshl_add_u64 v[224:225], s[22:23], 0, v[150:151]
	ds_read_b128 v[184:187], v175 offset:32768
	ds_read_b128 v[188:191], v175 offset:33792
	ds_read_b128 v[192:195], v175 offset:34816
	ds_read_b128 v[196:199], v175 offset:35840
	ds_read_b128 v[200:203], v175 offset:36864
	ds_read_b128 v[204:207], v175 offset:37888
	ds_read_b128 v[208:211], v175 offset:38912
	ds_read_b128 v[212:215], v175 offset:39936
	global_load_lds_dwordx4 v[224:225], off
	s_mov_b32 m0, s30
	v_lshl_add_u64 v[224:225], s[22:23], 0, v[146:147]
	global_load_lds_dwordx4 v[224:225], off
	s_waitcnt vmcnt(8)
	s_waitcnt lgkmcnt(0)
	s_barrier
	s_setprio 1
	s_waitcnt lgkmcnt(0)
	v_mfma_i32_16x16x64_i8 v[132:135], v[124:127], v[184:187], v[132:135]
	v_mfma_i32_16x16x64_i8 v[120:123], v[136:139], v[184:187], v[120:123]
	v_mfma_i32_16x16x64_i8 v[108:111], v[124:127], v[192:195], v[108:111]
	v_mfma_i32_16x16x64_i8 v[104:107], v[136:139], v[192:195], v[104:107]
	v_mfma_i32_16x16x64_i8 v[92:95], v[124:127], v[200:203], v[92:95]
	v_mfma_i32_16x16x64_i8 v[88:91], v[136:139], v[200:203], v[88:91]
	v_mfma_i32_16x16x64_i8 v[76:79], v[124:127], v[208:211], v[76:79]
	v_mfma_i32_16x16x64_i8 v[72:75], v[136:139], v[208:211], v[72:75]
	v_mfma_i32_16x16x64_i8 v[132:135], v[128:131], v[188:191], v[132:135]
	v_mfma_i32_16x16x64_i8 v[120:123], v[140:143], v[188:191], v[120:123]
	v_mfma_i32_16x16x64_i8 v[108:111], v[128:131], v[196:199], v[108:111]
	v_mfma_i32_16x16x64_i8 v[104:107], v[140:143], v[196:199], v[104:107]
	v_mfma_i32_16x16x64_i8 v[92:95], v[128:131], v[204:207], v[92:95]
	v_mfma_i32_16x16x64_i8 v[88:91], v[140:143], v[204:207], v[88:91]
	v_mfma_i32_16x16x64_i8 v[76:79], v[128:131], v[212:215], v[76:79]
	v_mfma_i32_16x16x64_i8 v[72:75], v[140:143], v[212:215], v[72:75]
	v_mfma_i32_16x16x64_i8 v[116:119], v[162:165], v[184:187], v[116:119]
	v_mfma_i32_16x16x64_i8 v[112:115], v[176:179], v[184:187], v[112:115]
	v_mfma_i32_16x16x64_i8 v[100:103], v[162:165], v[192:195], v[100:103]
	v_mfma_i32_16x16x64_i8 v[96:99], v[176:179], v[192:195], v[96:99]
	v_mfma_i32_16x16x64_i8 v[84:87], v[162:165], v[200:203], v[84:87]
	v_mfma_i32_16x16x64_i8 v[80:83], v[176:179], v[200:203], v[80:83]
	v_mfma_i32_16x16x64_i8 v[68:71], v[162:165], v[208:211], v[68:71]
	v_mfma_i32_16x16x64_i8 v[64:67], v[176:179], v[208:211], v[64:67]
	v_mfma_i32_16x16x64_i8 v[116:119], v[166:169], v[188:191], v[116:119]
	v_mfma_i32_16x16x64_i8 v[112:115], v[180:183], v[188:191], v[112:115]
	v_mfma_i32_16x16x64_i8 v[100:103], v[166:169], v[196:199], v[100:103]
	v_mfma_i32_16x16x64_i8 v[96:99], v[180:183], v[196:199], v[96:99]
	v_mfma_i32_16x16x64_i8 v[84:87], v[166:169], v[204:207], v[84:87]
	v_mfma_i32_16x16x64_i8 v[80:83], v[180:183], v[204:207], v[80:83]
	v_mfma_i32_16x16x64_i8 v[68:71], v[166:169], v[212:215], v[68:71]
	v_mfma_i32_16x16x64_i8 v[64:67], v[180:183], v[212:215], v[64:67]
	s_setprio 0
	s_barrier
	s_add_i32 s22, s45, s24
	v_lshl_add_u64 v[216:217], v[216:217], 0, s[12:13]
	s_mov_b32 m0, s22
	ds_read_b128 v[184:187], v175 offset:49152
	ds_read_b128 v[188:191], v175 offset:50176
	ds_read_b128 v[192:195], v175 offset:51200
	ds_read_b128 v[196:199], v175 offset:52224
	ds_read_b128 v[200:203], v175 offset:53248
	ds_read_b128 v[204:207], v175 offset:54272
	ds_read_b128 v[208:211], v175 offset:55296
	ds_read_b128 v[212:215], v175 offset:56320
	global_load_lds_dwordx4 v[216:217], off
	s_add_i32 m0, s22, 0x2000
	s_add_u32 s20, s20, 0x158080
	v_lshl_add_u64 v[216:217], v[218:219], 0, s[12:13]
	s_addc_u32 s21, s21, 0
	s_add_i32 s22, s46, s24
	global_load_lds_dwordx4 v[216:217], off
	s_mov_b32 m0, s22
	v_lshl_add_u64 v[216:217], s[20:21], 0, v[148:149]
	global_load_lds_dwordx4 v[216:217], off
	s_add_i32 m0, s22, 0x2000
	v_lshl_add_u64 v[216:217], s[20:21], 0, v[144:145]
	global_load_lds_dwordx4 v[216:217], off
	s_mov_b32 m0, s33
	v_lshl_add_u64 v[216:217], v[220:221], 0, s[12:13]
	global_load_lds_dwordx4 v[216:217], off
	s_mov_b32 m0, s34
	v_lshl_add_u64 v[216:217], v[222:223], 0, s[12:13]
	global_load_lds_dwordx4 v[216:217], off
	s_waitcnt vmcnt(8)
	s_waitcnt lgkmcnt(0)
	s_barrier
	s_setprio 1
	s_waitcnt lgkmcnt(0)
	v_mfma_i32_16x16x64_i8 v[60:63], v[124:127], v[184:187], v[60:63]
	v_mfma_i32_16x16x64_i8 v[56:59], v[136:139], v[184:187], v[56:59]
	v_mfma_i32_16x16x64_i8 v[44:47], v[124:127], v[192:195], v[44:47]
	v_mfma_i32_16x16x64_i8 v[40:43], v[136:139], v[192:195], v[40:43]
	v_mfma_i32_16x16x64_i8 v[28:31], v[124:127], v[200:203], v[28:31]
	v_mfma_i32_16x16x64_i8 v[24:27], v[136:139], v[200:203], v[24:27]
	v_mfma_i32_16x16x64_i8 v[12:15], v[124:127], v[208:211], v[12:15]
	v_mfma_i32_16x16x64_i8 v[8:11], v[136:139], v[208:211], v[8:11]
	v_mfma_i32_16x16x64_i8 v[60:63], v[128:131], v[188:191], v[60:63]
	v_mfma_i32_16x16x64_i8 v[56:59], v[140:143], v[188:191], v[56:59]
	v_mfma_i32_16x16x64_i8 v[44:47], v[128:131], v[196:199], v[44:47]
	v_mfma_i32_16x16x64_i8 v[40:43], v[140:143], v[196:199], v[40:43]
	v_mfma_i32_16x16x64_i8 v[28:31], v[128:131], v[204:207], v[28:31]
	v_mfma_i32_16x16x64_i8 v[24:27], v[140:143], v[204:207], v[24:27]
	v_mfma_i32_16x16x64_i8 v[12:15], v[128:131], v[212:215], v[12:15]
	v_mfma_i32_16x16x64_i8 v[8:11], v[140:143], v[212:215], v[8:11]
	v_mfma_i32_16x16x64_i8 v[52:55], v[162:165], v[184:187], v[52:55]
	v_mfma_i32_16x16x64_i8 v[48:51], v[176:179], v[184:187], v[48:51]
	v_mfma_i32_16x16x64_i8 v[36:39], v[162:165], v[192:195], v[36:39]
	v_mfma_i32_16x16x64_i8 v[32:35], v[176:179], v[192:195], v[32:35]
	v_mfma_i32_16x16x64_i8 v[20:23], v[162:165], v[200:203], v[20:23]
	v_mfma_i32_16x16x64_i8 v[16:19], v[176:179], v[200:203], v[16:19]
	v_mfma_i32_16x16x64_i8 v[4:7], v[162:165], v[208:211], v[4:7]
	v_mfma_i32_16x16x64_i8 v[0:3], v[176:179], v[208:211], v[0:3]
	v_mfma_i32_16x16x64_i8 v[52:55], v[166:169], v[188:191], v[52:55]
	v_mfma_i32_16x16x64_i8 v[48:51], v[180:183], v[188:191], v[48:51]
	v_mfma_i32_16x16x64_i8 v[36:39], v[166:169], v[196:199], v[36:39]
	v_mfma_i32_16x16x64_i8 v[32:35], v[180:183], v[196:199], v[32:35]
	v_mfma_i32_16x16x64_i8 v[20:23], v[166:169], v[204:207], v[20:23]
	v_mfma_i32_16x16x64_i8 v[16:19], v[180:183], v[204:207], v[16:19]
	v_mfma_i32_16x16x64_i8 v[4:7], v[166:169], v[212:215], v[4:7]
	v_mfma_i32_16x16x64_i8 v[0:3], v[180:183], v[212:215], v[0:3]
	s_setprio 0
	s_barrier
	s_add_i32 s44, s44, 2
	s_add_u32 s18, s18, 0x100
	s_addc_u32 s19, s19, 0
	s_add_u32 s42, s42, 0x100
	s_addc_u32 s43, s43, 0
	s_cmpk_lt_u32 s44, 0x54
	s_cbranch_scc1 .LBB0_1402
	s_nop 0
	s_nop 0
	s_nop 0
	s_nop 0
	s_nop 0
	s_nop 0
	s_nop 0
	s_nop 0
	s_nop 0
	s_nop 0
	s_nop 0
	s_nop 0
	s_nop 0
	s_nop 0
	s_nop 0
	s_nop 0
	s_andn2_b64 vcc, exec, s[14:15]
	s_cbranch_vccnz .LBB0_1405
	s_barrier
